# stack: scalar-base DMA + gz load batching + s5_pass1 next-tile prefetch + EpiRes global ops with counted waits
# speedup vs baseline: 1.0046x; 1.0007x over previous
; #define LAS __attribute__((address_space(3)))
; __device__ __forceinline__ void lds_fence() { asm volatile("s_waitcnt lgkmcnt(0)" ::: "memory"); }
; __device__ __forceinline__ f32x4 mfma16(bf16x8 a, bf16x8 b, f32x4 c) { return __builtin_amdgcn_mfma_f32_16x16x32_bf16(a, b, c, 0, 0, 0); }
; template <int PASS>
; __device__ __forceinline__ void s5_pass(CArgs& a, LAS unsigned char* lds, int l, int panel) {
;     ...
;     for (int gi = 0; gi < 2; ++gi) {
;         const int g = 2 * wave + gi;
;         const bf16_t* Wg = (const bf16_t*)(ws + WS_S5W) + (size_t)(l * 16 + g) * 128 * 64;
;         const bf16_t* Mg = (const bf16_t*)(ws + WS_S5M) + (size_t)(l * 16 + g) * 64 * 192;
;         bf16x8 wf[8][2];
; #pragma unroll
;         for (int mt = 0; mt < 8; ++mt)
; #pragma unroll
;             for (int ks = 0; ks < 2; ++ks) wf[mt][ks] = *(const bf16x8*)(Wg + (size_t)(16 * mt + fr) * 64 + 32 * ks + 8 * fq);
;         bf16x8 mf[4][4];
;         f32x4 dsk = (f32x4){0.f, 0.f, 0.f, 0.f};
;         if (PASS == 2) {
; #pragma unroll
;             for (int mt = 0; mt < 4; ++mt)
; #pragma unroll
;                 for (int ks = 0; ks < 4; ++ks) mf[mt][ks] = *(const bf16x8*)(Mg + (size_t)(16 * mt + fr) * 192 + 64 + 32 * ks + 8 * fq);
;             dsk = *(const f32x4*)(a.in[11] + l * 256 + g * 16 + 4 * fq);
;         }
;         const float* Ap = (const float*)(ws + WS_S5A) + ((size_t)(l * 16 + g) * 64 + lane) * 4;
;         const float a4r = Ap[0], a4i = Ap[1];
;         float* Hg = (float*)(ws + WS_S5H) + ((size_t)panel * 16 + g) * 128 + 2 * lane;
;         float Hr = 0.f, Hi = 0.f;
;         if (PASS == 2) { Hr = Hg[0]; Hi = Hg[1]; }
; #pragma unroll 1
;         for (int nt = 0; nt < 4; ++nt) {
;             bf16x8 xf[2];
; #pragma unroll
;             for (int ks = 0; ks < 2; ++ks) xf[ks] = *(const bf16x8*)(Zp + (size_t)(64 * nt + 4 * fr + 2 * ks + (fq >> 1)) * ZROWB + (C_S5U + g * 16 + (fq & 1) * 8) * 2);
; #pragma unroll
;             for (int mt = 0; mt < 8; ++mt) {
;                 f32x4 acc = mfma16(wf[mt][0], xf[0], (f32x4){0.f, 0.f, 0.f, 0.f});
;                 acc = mfma16(wf[mt][1], xf[1], acc);
;                 *(LAS f32x4*)(hl + fr * 128 + 16 * mt + 4 * fq) = acc;
;             }
;             lds_fence();
.LBB0_215:
	s_or_b64 exec, exec, s[2:3]
	v_readlane_b32 s2, v249, 0
	v_readlane_b32 s3, v249, 1
	s_load_dwordx2 s[2:3], s[2:3], 0xf8
	v_mov_b32_e32 v4, v189
	v_mov_b32_e32 v93, v1
	v_readfirstlane_b32 s1, v4
	s_ashr_i32 s4, s1, 6
	v_and_b32_e32 v5, 63, v4
	s_mul_i32 s5, s4, 0x3000
	s_lshl_b32 s10, s4, 1
	v_and_b32_e32 v92, 48, v4
	v_and_b32_e32 v77, 15, v4
	s_add_i32 s5, s5, 0
	s_waitcnt lgkmcnt(0)
	v_lshl_add_u64 v[2:3], s[2:3], 0, v[92:93]
	s_mov_b64 s[8:9], 0x3800000
	v_lshlrev_b32_e32 v0, 4, v5
	s_add_i32 s4, s10, s66
	v_lshl_add_u64 v[70:71], v[2:3], 0, s[8:9]
	v_lshl_add_u64 v[2:3], s[2:3], 0, v[0:1]
	s_mov_b64 s[8:9], 0x3100000
	v_lshl_add_u32 v81, v77, 9, s5
	v_lshl_add_u32 v75, v5, 3, s5
	s_ashr_i32 s5, s4, 31
	v_lshlrev_b32_e32 v68, 6, v77
	v_lshl_add_u64 v[66:67], v[2:3], 0, s[8:9]
	s_lshl_b64 s[8:9], s[4:5], 14
	v_lshl_add_u64 v[58:59], v[70:71], 0, s[8:9]
	v_lshlrev_b32_e32 v0, 7, v77
	v_or_b32_e32 v72, 0x800, v68
	v_lshl_add_u64 v[14:15], v[58:59], 0, v[0:1]
	v_lshlrev_b32_e32 v0, 1, v72
	v_or_b32_e32 v74, 0xc00, v68
	v_lshl_add_u64 v[22:23], v[58:59], 0, v[0:1]
	v_lshlrev_b32_e32 v0, 1, v74
	v_or_b32_e32 v76, 0x1000, v68
	v_lshl_add_u64 v[30:31], v[58:59], 0, v[0:1]
	v_lshlrev_b32_e32 v0, 1, v76
	v_or_b32_e32 v78, 0x1400, v68
	v_lshl_add_u64 v[38:39], v[58:59], 0, v[0:1]
	v_lshlrev_b32_e32 v0, 1, v78
	v_or_b32_e32 v82, 0x1800, v68
	v_lshl_add_u64 v[46:47], v[58:59], 0, v[0:1]
	v_lshlrev_b32_e32 v0, 1, v82
	v_or_b32_e32 v80, 0x1c00, v68
	v_lshl_add_u64 v[54:55], v[58:59], 0, v[0:1]
	v_lshlrev_b32_e32 v0, 1, v80
	s_lshl_b64 s[4:5], s[4:5], 10
	v_lshlrev_b32_e32 v73, 1, v5
	v_bfe_u32 v79, v4, 5, 1
	v_and_b32_e32 v69, 16, v4
	global_load_dwordx4 v[2:5], v[14:15], off
	global_load_dwordx4 v[6:9], v[14:15], off offset:64
	global_load_dwordx4 v[10:13], v[14:15], off offset:2048
	s_nop 0
	global_load_dwordx4 v[14:17], v[14:15], off offset:2112
	v_lshl_add_u64 v[62:63], v[58:59], 0, v[0:1]
	v_lshl_add_u64 v[84:85], v[66:67], 0, s[4:5]
	global_load_dwordx4 v[18:21], v[22:23], off
	s_nop 0
	global_load_dwordx4 v[22:25], v[22:23], off offset:64
	s_nop 0
	global_load_dwordx4 v[26:29], v[30:31], off
	s_nop 0
	global_load_dwordx4 v[30:33], v[30:31], off offset:64
	s_nop 0
	global_load_dwordx4 v[34:37], v[38:39], off
	s_nop 0
	global_load_dwordx4 v[38:41], v[38:39], off offset:64
	s_nop 0
	global_load_dwordx4 v[42:45], v[46:47], off
	s_nop 0
	global_load_dwordx4 v[46:49], v[46:47], off offset:64
	s_nop 0
	global_load_dwordx4 v[50:53], v[54:55], off
	s_nop 0
	global_load_dwordx4 v[54:57], v[54:55], off offset:64
	s_nop 0
	global_load_dwordx4 v[58:61], v[62:63], off
	s_nop 0
	global_load_dwordx4 v[62:65], v[62:63], off offset:64
	s_andn2_b32 s1, s1, 63
	global_load_dwordx2 v[84:85], v[84:85], off
	v_or_b32_e32 v88, s1, v69
	v_mul_u32_u24_e32 v0, 0x1400, v79
	s_add_u32 s26, s2, s88
	v_ashrrev_i32_e32 v89, 31, v88
	v_mad_u32_u24 v0, v77, s62, v0
	s_addc_u32 s27, s3, s89
	v_lshl_add_u64 v[88:89], v[88:89], 0, v[0:1]
	v_mov_b32_e32 v90, 0
	v_lshl_add_u64 v[88:89], s[26:27], 0, v[88:89]
	s_mov_b64 s[38:39], 0
	v_add_u32_e32 v77, v81, v92
	v_mov_b32_e32 v91, v90
	s_waitcnt vmcnt(0)
	v_pk_mov_b32 v[86:87], v[84:85], v[84:85] op_sel:[1,0]
	v_add_co_u32_e32 v104, vcc, 0xe000000, v88
	s_nop 1
	v_addc_co_u32_e32 v105, vcc, 0, v89, vcc
	global_load_dwordx4 v[104:107], v[104:105], off
	v_add_co_u32_e32 v108, vcc, 0xe002000, v88
	s_nop 1
	v_addc_co_u32_e32 v109, vcc, 0, v89, vcc
	global_load_dwordx4 v[108:111], v[108:109], off offset:2048
.LBB0_216:
	s_waitcnt vmcnt(0)
	v_mov_b64_e32 v[92:93], v[104:105]
	v_mov_b64_e32 v[94:95], v[106:107]
	v_mov_b64_e32 v[96:97], v[108:109]
	v_mov_b64_e32 v[98:99], v[110:111]
	s_add_u32 s38, s38, 0x50000
	s_addc_u32 s39, s39, 0
	v_lshl_add_u64 v[112:113], v[88:89], 0, s[38:39]
	v_add_co_u32_e32 v104, vcc, 0xe000000, v112
	s_nop 1
	v_addc_co_u32_e32 v105, vcc, 0, v113, vcc
	global_load_dwordx4 v[104:107], v[104:105], off
	v_add_co_u32_e32 v108, vcc, 0xe002000, v112
	s_nop 1
	v_addc_co_u32_e32 v109, vcc, 0, v113, vcc
	global_load_dwordx4 v[108:111], v[108:109], off offset:2048
	s_cmp_lg_u32 s38, 0x140000
	v_mfma_f32_16x16x32_bf16 v[100:103], v[2:5], v[92:95], 0
	v_mfma_f32_16x16x32_bf16 v[100:103], v[6:9], v[96:99], v[100:103]
	s_nop 7
	ds_write_b128 v77, v[100:103]
	v_mfma_f32_16x16x32_bf16 v[100:103], v[10:13], v[92:95], 0
	v_mfma_f32_16x16x32_bf16 v[100:103], v[14:17], v[96:99], v[100:103]
	s_nop 7
	ds_write_b128 v77, v[100:103] offset:64
	v_mfma_f32_16x16x32_bf16 v[100:103], v[18:21], v[92:95], 0
	v_mfma_f32_16x16x32_bf16 v[100:103], v[22:25], v[96:99], v[100:103]
	s_nop 7
	ds_write_b128 v77, v[100:103] offset:128
	v_mfma_f32_16x16x32_bf16 v[100:103], v[26:29], v[92:95], 0
	v_mfma_f32_16x16x32_bf16 v[100:103], v[30:33], v[96:99], v[100:103]
	s_nop 7
	ds_write_b128 v77, v[100:103] offset:192
	v_mfma_f32_16x16x32_bf16 v[100:103], v[34:37], v[92:95], 0
	v_mfma_f32_16x16x32_bf16 v[100:103], v[38:41], v[96:99], v[100:103]
	s_nop 7
	ds_write_b128 v77, v[100:103] offset:256
	v_mfma_f32_16x16x32_bf16 v[100:103], v[42:45], v[92:95], 0
	v_mfma_f32_16x16x32_bf16 v[100:103], v[46:49], v[96:99], v[100:103]
	s_nop 7
	ds_write_b128 v77, v[100:103] offset:320
	v_mfma_f32_16x16x32_bf16 v[100:103], v[50:53], v[92:95], 0
	v_mfma_f32_16x16x32_bf16 v[92:95], v[58:61], v[92:95], 0
	v_mfma_f32_16x16x32_bf16 v[100:103], v[54:57], v[96:99], v[100:103]
	v_mfma_f32_16x16x32_bf16 v[92:95], v[62:65], v[96:99], v[92:95]
	v_mul_f32_e32 v96, v85, v91
	s_nop 5
	ds_write_b128 v77, v[100:103] offset:384
	v_pk_fma_f32 v[96:97], v[84:85], v[90:91], v[96:97] op_sel_hi:[1,1,0] neg_lo:[0,0,1] neg_hi:[0,0,1]
	v_pk_mul_f32 v[90:91], v[86:87], v[90:91]
	s_nop 0
	v_add_f32_e32 v90, v90, v91
	ds_write_b128 v77, v[92:95] offset:448
	s_waitcnt lgkmcnt(0)
; #define LAS __attribute__((address_space(3)))
; __device__ __forceinline__ unsigned pk2(float lo, float hi) { unsigned r; asm("v_cvt_pk_bf16_f32 %0, %1, %2" : "=v"(r) : "v"(lo), "v"(hi)); return r; }
; template <int PASS>
; __device__ __forceinline__ void s5_pass(CArgs& a, LAS unsigned char* lds, int l, int panel) {
;     ...
;             for (int j = 0; j < 16; ++j) {
;                 if (PASS == 2) *(LAS unsigned*)(xh + j * 128 + 2 * lane) = pk2(Hr, Hi);
;                 const f32x2 lc = *(LAS f32x2*)(hl + j * 128 + 2 * lane);
;                 const float nr = a4r * Hr - a4i * Hi + lc.x, ni = a4r * Hi + a4i * Hr + lc.y;
;                 Hr = nr; Hi = ni;
;             }
	ds_read2st64_b64 v[92:95], v75 offset1:1
	s_waitcnt lgkmcnt(0)
	v_pk_add_f32 v[90:91], v[90:91], v[92:93] op_sel:[0,1] op_sel_hi:[0,1]
	v_pk_add_f32 v[100:101], v[96:97], v[92:93]
	v_pk_mul_f32 v[90:91], v[86:87], v[90:91]
	ds_read2st64_b64 v[96:99], v75 offset0:2 offset1:3
	v_pk_fma_f32 v[92:93], v[84:85], v[100:101], v[90:91] neg_lo:[0,0,1] neg_hi:[0,0,1]
	v_pk_fma_f32 v[90:91], v[84:85], v[100:101], v[90:91] op_sel_hi:[1,0,1]
	s_nop 0
	v_mov_b32_e32 v93, v91
	v_pk_add_f32 v[90:91], v[94:95], v[92:93]
	s_nop 0
	v_mul_f32_e32 v92, v85, v91
	v_pk_mul_f32 v[100:101], v[84:85], v[90:91] op_sel:[0,1] op_sel_hi:[1,0]
	v_pk_fma_f32 v[92:93], v[84:85], v[90:91], v[92:93] op_sel_hi:[1,1,0] neg_lo:[0,0,1] neg_hi:[0,0,1]
	v_add_f32_e32 v100, v100, v101
	s_waitcnt lgkmcnt(0)
	v_pk_add_f32 v[94:95], v[96:97], v[92:93]
	v_pk_add_f32 v[96:97], v[96:97], v[100:101] op_sel:[1,0] op_sel_hi:[1,0]
	ds_read2st64_b64 v[90:93], v75 offset0:4 offset1:5
	v_pk_mul_f32 v[96:97], v[86:87], v[96:97]
	s_nop 0
	v_pk_fma_f32 v[100:101], v[84:85], v[94:95], v[96:97] neg_lo:[0,0,1] neg_hi:[0,0,1]
	v_pk_fma_f32 v[94:95], v[84:85], v[94:95], v[96:97] op_sel_hi:[1,0,1]
	s_nop 0
	v_mov_b32_e32 v101, v95
	v_pk_add_f32 v[94:95], v[98:99], v[100:101]
	s_nop 0
	v_mul_f32_e32 v96, v85, v95
	v_pk_mul_f32 v[100:101], v[84:85], v[94:95] op_sel:[0,1] op_sel_hi:[1,0]
	v_pk_fma_f32 v[96:97], v[84:85], v[94:95], v[96:97] op_sel_hi:[1,1,0] neg_lo:[0,0,1] neg_hi:[0,0,1]
	v_add_f32_e32 v100, v100, v101
	s_waitcnt lgkmcnt(0)
	v_pk_add_f32 v[98:99], v[90:91], v[96:97]
	v_pk_add_f32 v[90:91], v[90:91], v[100:101] op_sel:[1,0] op_sel_hi:[1,0]
	ds_read2st64_b64 v[94:97], v75 offset0:6 offset1:7
	v_pk_mul_f32 v[90:91], v[86:87], v[90:91]
	s_nop 0
	v_pk_fma_f32 v[100:101], v[84:85], v[98:99], v[90:91] neg_lo:[0,0,1] neg_hi:[0,0,1]
	v_pk_fma_f32 v[90:91], v[84:85], v[98:99], v[90:91] op_sel_hi:[1,0,1]
	s_nop 0
	v_mov_b32_e32 v101, v91
	v_pk_add_f32 v[90:91], v[92:93], v[100:101]
	s_nop 0
	v_mul_f32_e32 v92, v85, v91
	v_pk_mul_f32 v[100:101], v[84:85], v[90:91] op_sel:[0,1] op_sel_hi:[1,0]
	v_pk_fma_f32 v[92:93], v[84:85], v[90:91], v[92:93] op_sel_hi:[1,1,0] neg_lo:[0,0,1] neg_hi:[0,0,1]
	v_add_f32_e32 v100, v100, v101
	s_waitcnt lgkmcnt(0)
	v_pk_add_f32 v[98:99], v[94:95], v[92:93]
	v_pk_add_f32 v[94:95], v[94:95], v[100:101] op_sel:[1,0] op_sel_hi:[1,0]
	ds_read2st64_b64 v[90:93], v75 offset0:8 offset1:9
	v_pk_mul_f32 v[94:95], v[86:87], v[94:95]
	s_nop 0
	v_pk_fma_f32 v[100:101], v[84:85], v[98:99], v[94:95] neg_lo:[0,0,1] neg_hi:[0,0,1]
	v_pk_fma_f32 v[94:95], v[84:85], v[98:99], v[94:95] op_sel_hi:[1,0,1]
	s_nop 0
	v_mov_b32_e32 v101, v95
	v_pk_add_f32 v[94:95], v[96:97], v[100:101]
	s_nop 0
	v_mul_f32_e32 v96, v85, v95
	v_pk_mul_f32 v[100:101], v[84:85], v[94:95] op_sel:[0,1] op_sel_hi:[1,0]
	v_pk_fma_f32 v[96:97], v[84:85], v[94:95], v[96:97] op_sel_hi:[1,1,0] neg_lo:[0,0,1] neg_hi:[0,0,1]
	v_add_f32_e32 v100, v100, v101
	s_waitcnt lgkmcnt(0)
	v_pk_add_f32 v[98:99], v[90:91], v[96:97]
	v_pk_add_f32 v[90:91], v[90:91], v[100:101] op_sel:[1,0] op_sel_hi:[1,0]
	ds_read2st64_b64 v[94:97], v75 offset0:10 offset1:11
	v_pk_mul_f32 v[90:91], v[86:87], v[90:91]
	s_nop 0
	v_pk_fma_f32 v[100:101], v[84:85], v[98:99], v[90:91] neg_lo:[0,0,1] neg_hi:[0,0,1]
	v_pk_fma_f32 v[90:91], v[84:85], v[98:99], v[90:91] op_sel_hi:[1,0,1]
	s_nop 0
	v_mov_b32_e32 v101, v91
	v_pk_add_f32 v[90:91], v[92:93], v[100:101]
	s_nop 0
	v_mul_f32_e32 v92, v85, v91
	v_pk_mul_f32 v[100:101], v[84:85], v[90:91] op_sel:[0,1] op_sel_hi:[1,0]
	v_pk_fma_f32 v[92:93], v[84:85], v[90:91], v[92:93] op_sel_hi:[1,1,0] neg_lo:[0,0,1] neg_hi:[0,0,1]
	v_add_f32_e32 v100, v100, v101
	s_waitcnt lgkmcnt(0)
	v_pk_add_f32 v[98:99], v[94:95], v[92:93]
	v_pk_add_f32 v[94:95], v[94:95], v[100:101] op_sel:[1,0] op_sel_hi:[1,0]
	ds_read2st64_b64 v[90:93], v75 offset0:12 offset1:13
	v_pk_mul_f32 v[94:95], v[86:87], v[94:95]
	s_nop 0
	v_pk_fma_f32 v[100:101], v[84:85], v[98:99], v[94:95] neg_lo:[0,0,1] neg_hi:[0,0,1]
	v_pk_fma_f32 v[94:95], v[84:85], v[98:99], v[94:95] op_sel_hi:[1,0,1]
	s_nop 0
	v_mov_b32_e32 v101, v95
	v_pk_add_f32 v[94:95], v[96:97], v[100:101]
	s_nop 0
	v_mul_f32_e32 v96, v85, v95
	v_pk_mul_f32 v[100:101], v[84:85], v[94:95] op_sel:[0,1] op_sel_hi:[1,0]
	v_pk_fma_f32 v[96:97], v[84:85], v[94:95], v[96:97] op_sel_hi:[1,1,0] neg_lo:[0,0,1] neg_hi:[0,0,1]
	v_add_f32_e32 v100, v100, v101
	s_waitcnt lgkmcnt(0)
	v_pk_add_f32 v[98:99], v[90:91], v[96:97]
	v_pk_add_f32 v[90:91], v[90:91], v[100:101] op_sel:[1,0] op_sel_hi:[1,0]
	ds_read2st64_b64 v[94:97], v75 offset0:14 offset1:15
	v_pk_mul_f32 v[90:91], v[86:87], v[90:91]
	s_waitcnt lgkmcnt(0)
	s_waitcnt lgkmcnt(0)
	s_nop 0
	v_pk_fma_f32 v[100:101], v[84:85], v[98:99], v[90:91] neg_lo:[0,0,1] neg_hi:[0,0,1]
	v_pk_fma_f32 v[90:91], v[84:85], v[98:99], v[90:91] op_sel_hi:[1,0,1]
	s_nop 0
	v_mov_b32_e32 v101, v91
	v_pk_add_f32 v[90:91], v[92:93], v[100:101]
	s_nop 0
	v_mul_f32_e32 v92, v85, v91
	v_pk_fma_f32 v[92:93], v[84:85], v[90:91], v[92:93] op_sel_hi:[1,1,0] neg_lo:[0,0,1] neg_hi:[0,0,1]
	v_pk_mul_f32 v[90:91], v[84:85], v[90:91] op_sel:[0,1] op_sel_hi:[1,0]
	s_waitcnt lgkmcnt(0)
	v_pk_add_f32 v[92:93], v[94:95], v[92:93]
	v_add_f32_e32 v90, v90, v91
	v_pk_add_f32 v[90:91], v[94:95], v[90:91] op_sel:[1,0] op_sel_hi:[1,0]
	s_nop 0
	v_pk_mul_f32 v[90:91], v[86:87], v[90:91]
	s_nop 0
	v_pk_fma_f32 v[94:95], v[84:85], v[92:93], v[90:91] neg_lo:[0,0,1] neg_hi:[0,0,1]
	v_pk_fma_f32 v[90:91], v[84:85], v[92:93], v[90:91] op_sel_hi:[1,0,1]
	s_nop 0
	v_mov_b32_e32 v95, v91
	v_pk_add_f32 v[90:91], v[96:97], v[94:95]
	s_cbranch_scc1 .LBB0_216
; #define LAS __attribute__((address_space(3)))
; __device__ __forceinline__ void lds_fence() { asm volatile("s_waitcnt lgkmcnt(0)" ::: "memory"); }
; __device__ __forceinline__ f32x4 mfma16(bf16x8 a, bf16x8 b, f32x4 c) { return __builtin_amdgcn_mfma_f32_16x16x32_bf16(a, b, c, 0, 0, 0); }
; template <int PASS>
; __device__ __forceinline__ void s5_pass(CArgs& a, LAS unsigned char* lds, int l, int panel) {
;     ...
;     for (int gi = 0; gi < 2; ++gi) {
;         const int g = 2 * wave + gi;
;         const bf16_t* Wg = (const bf16_t*)(ws + WS_S5W) + (size_t)(l * 16 + g) * 128 * 64;
;         const bf16_t* Mg = (const bf16_t*)(ws + WS_S5M) + (size_t)(l * 16 + g) * 64 * 192;
;         bf16x8 wf[8][2];
; #pragma unroll
;         for (int mt = 0; mt < 8; ++mt)
; #pragma unroll
;             for (int ks = 0; ks < 2; ++ks) wf[mt][ks] = *(const bf16x8*)(Wg + (size_t)(16 * mt + fr) * 64 + 32 * ks + 8 * fq);
;         bf16x8 mf[4][4];
;         f32x4 dsk = (f32x4){0.f, 0.f, 0.f, 0.f};
;         if (PASS == 2) {
; #pragma unroll
;             for (int mt = 0; mt < 4; ++mt)
; #pragma unroll
;                 for (int ks = 0; ks < 4; ++ks) mf[mt][ks] = *(const bf16x8*)(Mg + (size_t)(16 * mt + fr) * 192 + 64 + 32 * ks + 8 * fq);
;             dsk = *(const f32x4*)(a.in[11] + l * 256 + g * 16 + 4 * fq);
;         }
;         const float* Ap = (const float*)(ws + WS_S5A) + ((size_t)(l * 16 + g) * 64 + lane) * 4;
;         const float a4r = Ap[0], a4i = Ap[1];
;         float* Hg = (float*)(ws + WS_S5H) + ((size_t)panel * 16 + g) * 128 + 2 * lane;
;         float Hr = 0.f, Hi = 0.f;
;         if (PASS == 2) { Hr = Hg[0]; Hi = Hg[1]; }
; #pragma unroll 1
;         for (int nt = 0; nt < 4; ++nt) {
;             bf16x8 xf[2];
; #pragma unroll
;             for (int ks = 0; ks < 2; ++ks) xf[ks] = *(const bf16x8*)(Zp + (size_t)(64 * nt + 4 * fr + 2 * ks + (fq >> 1)) * ZROWB + (C_S5U + g * 16 + (fq & 1) * 8) * 2);
; #pragma unroll
;             for (int mt = 0; mt < 8; ++mt) {
;                 f32x4 acc = mfma16(wf[mt][0], xf[0], (f32x4){0.f, 0.f, 0.f, 0.f});
;                 acc = mfma16(wf[mt][1], xf[1], acc);
;                 *(LAS f32x4*)(hl + fr * 128 + 16 * mt + 4 * fq) = acc;
;             }
;             lds_fence();
;     ...
;         if (PASS == 1) { Hg[0] = Hr; Hg[1] = Hi; }
	s_waitcnt vmcnt(0)
	v_readlane_b32 s4, v248, 3
	v_readlane_b32 s5, v248, 4
	s_add_u32 s2, s2, s4
	s_addc_u32 s3, s3, s5
	v_lshlrev_b32_e32 v2, 2, v73
	v_mov_b32_e32 v3, v1
	v_lshl_add_u64 v[2:3], s[2:3], 0, v[2:3]
	s_mov_b64 s[2:3], 0x3b00000
	s_ashr_i32 s11, s10, 31
	v_lshl_add_u64 v[84:85], v[2:3], 0, s[2:3]
	s_lshl_b64 s[2:3], s[10:11], 9
	v_lshl_add_u64 v[2:3], v[84:85], 0, s[2:3]
	s_or_b32 s2, s10, 1
	s_add_i32 s4, s2, s66
	s_ashr_i32 s5, s4, 31
	s_lshl_b64 s[8:9], s[4:5], 14
	global_store_dwordx2 v[2:3], v[90:91], off
	v_lshl_add_u64 v[58:59], v[70:71], 0, s[8:9]
	v_lshlrev_b32_e32 v2, 1, v68
	v_mov_b32_e32 v3, v1
	v_lshl_add_u64 v[14:15], v[58:59], 0, v[2:3]
	global_load_dwordx4 v[2:5], v[14:15], off
	global_load_dwordx4 v[6:9], v[14:15], off offset:64
	global_load_dwordx4 v[10:13], v[14:15], off offset:2048
	s_nop 0
	global_load_dwordx4 v[14:17], v[14:15], off offset:2112
	v_lshlrev_b32_e32 v18, 1, v72
	v_mov_b32_e32 v19, v1
	v_lshlrev_b32_e32 v26, 1, v74
	v_mov_b32_e32 v27, v1
	v_lshlrev_b32_e32 v34, 1, v76
	v_mov_b32_e32 v35, v1
	v_lshlrev_b32_e32 v42, 1, v78
	v_mov_b32_e32 v43, v1
	v_lshlrev_b32_e32 v50, 1, v82
	v_mov_b32_e32 v51, v1
	v_lshl_add_u64 v[22:23], v[58:59], 0, v[18:19]
	v_lshl_add_u64 v[30:31], v[58:59], 0, v[26:27]
	v_lshl_add_u64 v[38:39], v[58:59], 0, v[34:35]
	v_lshl_add_u64 v[46:47], v[58:59], 0, v[42:43]
	v_lshl_add_u64 v[54:55], v[58:59], 0, v[50:51]
	v_lshlrev_b32_e32 v60, 1, v80
	v_mov_b32_e32 v61, v1
	s_lshl_b64 s[4:5], s[4:5], 10
	global_load_dwordx4 v[18:21], v[22:23], off
	s_nop 0
	global_load_dwordx4 v[22:25], v[22:23], off offset:64
	s_nop 0
	global_load_dwordx4 v[26:29], v[30:31], off
	s_nop 0
	global_load_dwordx4 v[30:33], v[30:31], off offset:64
	s_nop 0
	global_load_dwordx4 v[34:37], v[38:39], off
	s_nop 0
	global_load_dwordx4 v[38:41], v[38:39], off offset:64
	s_nop 0
	global_load_dwordx4 v[42:45], v[46:47], off
	s_nop 0
	global_load_dwordx4 v[46:49], v[46:47], off offset:64
	s_nop 0
	global_load_dwordx4 v[50:53], v[54:55], off
	s_nop 0
	global_load_dwordx4 v[54:57], v[54:55], off offset:64
	v_lshl_add_u64 v[62:63], v[58:59], 0, v[60:61]
	v_lshl_add_u64 v[58:59], v[66:67], 0, s[4:5]
	global_load_dwordx2 v[66:67], v[58:59], off
	s_nop 0
	global_load_dwordx4 v[58:61], v[62:63], off
	s_nop 0
	global_load_dwordx4 v[62:65], v[62:63], off offset:64
	v_lshl_or_b32 v68, s2, 5, v69
	v_ashrrev_i32_e32 v69, 31, v68
	v_mov_b32_e32 v72, 0
	v_lshl_add_u64 v[68:69], v[68:69], 0, v[0:1]
	s_mov_b64 s[10:11], 0
	v_lshl_add_u64 v[68:69], s[26:27], 0, v[68:69]
	v_mov_b32_e32 v73, v72
	s_waitcnt vmcnt(2)
	v_pk_mov_b32 v[70:71], v[66:67], v[66:67] op_sel:[1,0]
	v_add_co_u32_e32 v104, vcc, 0xe000000, v68
	s_nop 1
	v_addc_co_u32_e32 v105, vcc, 0, v69, vcc
	global_load_dwordx4 v[104:107], v[104:105], off
	v_add_co_u32_e32 v108, vcc, 0xe002000, v68
	s_nop 1
	v_addc_co_u32_e32 v109, vcc, 0, v69, vcc
	global_load_dwordx4 v[108:111], v[108:109], off offset:2048
.LBB0_218:
	s_waitcnt vmcnt(0)
	v_mov_b64_e32 v[78:79], v[104:105]
	v_mov_b64_e32 v[80:81], v[106:107]
	v_mov_b64_e32 v[86:87], v[108:109]
	v_mov_b64_e32 v[88:89], v[110:111]
	v_mul_f32_e32 v0, v67, v73
	s_add_u32 s10, s10, 0x50000
	s_addc_u32 s11, s11, 0
	v_lshl_add_u64 v[112:113], v[68:69], 0, s[10:11]
	v_add_co_u32_e32 v104, vcc, 0xe000000, v112
	s_nop 1
	v_addc_co_u32_e32 v105, vcc, 0, v113, vcc
	global_load_dwordx4 v[104:107], v[104:105], off
	v_add_co_u32_e32 v108, vcc, 0xe002000, v112
	s_nop 1
	v_addc_co_u32_e32 v109, vcc, 0, v113, vcc
	global_load_dwordx4 v[108:111], v[108:109], off offset:2048
	v_pk_fma_f32 v[82:83], v[66:67], v[72:73], v[0:1] op_sel_hi:[1,1,0] neg_lo:[0,0,1] neg_hi:[0,0,1]
	v_pk_mul_f32 v[72:73], v[70:71], v[72:73]
	v_add_f32_e32 v0, v72, v73
	s_cmp_lg_u32 s10, 0x140000
	v_mfma_f32_16x16x32_bf16 v[90:93], v[2:5], v[78:81], 0
	v_mfma_f32_16x16x32_bf16 v[90:93], v[6:9], v[86:89], v[90:93]
	s_nop 7
	ds_write_b128 v77, v[90:93]
	v_mfma_f32_16x16x32_bf16 v[90:93], v[10:13], v[78:81], 0
	v_mfma_f32_16x16x32_bf16 v[90:93], v[14:17], v[86:89], v[90:93]
	s_nop 7
	ds_write_b128 v77, v[90:93] offset:64
	v_mfma_f32_16x16x32_bf16 v[90:93], v[18:21], v[78:81], 0
	v_mfma_f32_16x16x32_bf16 v[90:93], v[22:25], v[86:89], v[90:93]
	s_nop 7
	ds_write_b128 v77, v[90:93] offset:128
	v_mfma_f32_16x16x32_bf16 v[90:93], v[26:29], v[78:81], 0
	v_mfma_f32_16x16x32_bf16 v[90:93], v[30:33], v[86:89], v[90:93]
	s_nop 7
	ds_write_b128 v77, v[90:93] offset:192
	v_mfma_f32_16x16x32_bf16 v[90:93], v[34:37], v[78:81], 0
	v_mfma_f32_16x16x32_bf16 v[90:93], v[38:41], v[86:89], v[90:93]
	s_nop 7
	ds_write_b128 v77, v[90:93] offset:256
	v_mfma_f32_16x16x32_bf16 v[90:93], v[42:45], v[78:81], 0
	v_mfma_f32_16x16x32_bf16 v[90:93], v[46:49], v[86:89], v[90:93]
	s_nop 7
	ds_write_b128 v77, v[90:93] offset:320
	v_mfma_f32_16x16x32_bf16 v[90:93], v[50:53], v[78:81], 0
	v_mfma_f32_16x16x32_bf16 v[78:81], v[58:61], v[78:81], 0
	v_mfma_f32_16x16x32_bf16 v[90:93], v[54:57], v[86:89], v[90:93]
	v_mfma_f32_16x16x32_bf16 v[78:81], v[62:65], v[86:89], v[78:81]
	s_nop 6
	ds_write_b128 v77, v[90:93] offset:384
	ds_write_b128 v77, v[78:81] offset:448
	s_waitcnt lgkmcnt(0)
	ds_read2st64_b64 v[78:81], v75 offset1:1
	ds_read2st64_b64 v[86:89], v75 offset0:2 offset1:3
	s_waitcnt lgkmcnt(1)
	v_pk_add_f32 v[72:73], v[0:1], v[78:79] op_sel:[0,1] op_sel_hi:[0,1]
	v_pk_add_f32 v[82:83], v[82:83], v[78:79]
	v_pk_mul_f32 v[72:73], v[70:71], v[72:73]
	s_nop 0
	v_pk_fma_f32 v[78:79], v[66:67], v[82:83], v[72:73] neg_lo:[0,0,1] neg_hi:[0,0,1]
	v_pk_fma_f32 v[72:73], v[66:67], v[82:83], v[72:73] op_sel_hi:[1,0,1]
	s_nop 0
	v_mov_b32_e32 v79, v73
	v_pk_add_f32 v[72:73], v[80:81], v[78:79]
	s_nop 0
	v_mul_f32_e32 v0, v67, v73
	v_pk_fma_f32 v[78:79], v[66:67], v[72:73], v[0:1] op_sel_hi:[1,1,0] neg_lo:[0,0,1] neg_hi:[0,0,1]
	v_pk_mul_f32 v[72:73], v[66:67], v[72:73] op_sel:[0,1] op_sel_hi:[1,0]
	s_waitcnt lgkmcnt(0)
; #define LAS __attribute__((address_space(3)))
; template <int PASS>
; __device__ __forceinline__ void s5_pass(CArgs& a, LAS unsigned char* lds, int l, int panel) {
;     ...
;             for (int j = 0; j < 16; ++j) {
;                 if (PASS == 2) *(LAS unsigned*)(xh + j * 128 + 2 * lane) = pk2(Hr, Hi);
;                 const f32x2 lc = *(LAS f32x2*)(hl + j * 128 + 2 * lane);
;                 const float nr = a4r * Hr - a4i * Hi + lc.x, ni = a4r * Hi + a4i * Hr + lc.y;
;                 Hr = nr; Hi = ni;
;             }
;             lds_fence();
;             if (PASS == 2) {
;                 bf16x8 xhf[4];
; #pragma unroll
;                 for (int k4 = 0; k4 < 4; ++k4) xhf[k4] = *(const LAS bf16x8*)(xh + fr * 128 + 32 * k4 + 8 * fq);
; #pragma unroll
;                 for (int mt = 0; mt < 4; ++mt) {
;                     f32x4 acc = (f32x4){0.f, 0.f, 0.f, 0.f};
; #pragma unroll
;                     for (int ks = 0; ks < 2; ++ks) if (2 * ks <= mt) acc = mfma16(*(const bf16x8*)(Mg + (size_t)(16 * mt + fr) * 192 + 32 * ks + 8 * fq), xf[ks], acc);
; #pragma unroll
;                     for (int k4 = 0; k4 < 4; ++k4) acc = mfma16(mf[mt][k4], xhf[k4], acc);
;                     const int tok = (16 * nt + fr) * 4 + mt, ch = g * 16 + 4 * fq;
;                     const u32x2 uv = *(const u32x2*)(Zp + (size_t)tok * ZROWB + (C_S5U + ch) * 2);
;                     const float y0 = gelu_tanh(acc[0] + dsk[0] * bflo(uv.x)), y1 = gelu_tanh(acc[1] + dsk[1] * bfhi(uv.x));
;                     const float y2 = gelu_tanh(acc[2] + dsk[2] * bflo(uv.y)), y3 = gelu_tanh(acc[3] + dsk[3] * bfhi(uv.y));
;                     u32x2 w; w.x = pk2(y0, y1); w.y = pk2(y2, y3);
;                     *(u32x2*)(YS5 + (size_t)tok * 512 + ch * 2) = w;
;                 }
;             }
;             lds_fence();
;         }
;         if (PASS == 1) { Hg[0] = Hr; Hg[1] = Hi; }
; template <int PASS>
; __device__ __forceinline__ void gla_pass(CArgs& a, LAS unsigned char* lds, int l, int panel) {
;     ...
;     const unsigned char* Zp = ws + WS_PANEL + (size_t)panel * PANEL_BYTES + P_Z;
;     unsigned char* MIX = ws + WS_PANEL + (size_t)panel * PANEL_BYTES + P_MIX;
;     LAS float* GP = (LAS float*)(lds + GL_GP); LAS float* SS = (LAS float*)(lds + GL_SS); LAS float* DK = (LAS float*)(lds + GL_DK);
;     u32x4 pgz[2]; bf16_t pq[8], pk[8]; unsigned pv[8]; u32x2 pr[4];
	v_pk_add_f32 v[82:83], v[86:87], v[78:79]
	v_add_f32_e32 v0, v72, v73
	v_pk_add_f32 v[72:73], v[86:87], v[0:1] op_sel:[1,0] op_sel_hi:[1,0]
	ds_read2st64_b64 v[78:81], v75 offset0:4 offset1:5
	v_pk_mul_f32 v[72:73], v[70:71], v[72:73]
	s_nop 0
	v_pk_fma_f32 v[86:87], v[66:67], v[82:83], v[72:73] neg_lo:[0,0,1] neg_hi:[0,0,1]
	v_pk_fma_f32 v[72:73], v[66:67], v[82:83], v[72:73] op_sel_hi:[1,0,1]
	s_nop 0
	v_mov_b32_e32 v87, v73
	v_pk_add_f32 v[72:73], v[88:89], v[86:87]
	ds_read2st64_b64 v[86:89], v75 offset0:6 offset1:7
	v_mul_f32_e32 v0, v67, v73
	v_pk_fma_f32 v[82:83], v[66:67], v[72:73], v[0:1] op_sel_hi:[1,1,0] neg_lo:[0,0,1] neg_hi:[0,0,1]
	v_pk_mul_f32 v[72:73], v[66:67], v[72:73] op_sel:[0,1] op_sel_hi:[1,0]
	s_waitcnt lgkmcnt(1)
	v_pk_add_f32 v[82:83], v[78:79], v[82:83]
	v_add_f32_e32 v0, v72, v73
	v_pk_add_f32 v[72:73], v[78:79], v[0:1] op_sel:[1,0] op_sel_hi:[1,0]
	s_nop 0
	v_pk_mul_f32 v[72:73], v[70:71], v[72:73]
	s_nop 0
	v_pk_fma_f32 v[78:79], v[66:67], v[82:83], v[72:73] neg_lo:[0,0,1] neg_hi:[0,0,1]
	v_pk_fma_f32 v[72:73], v[66:67], v[82:83], v[72:73] op_sel_hi:[1,0,1]
	s_nop 0
	v_mov_b32_e32 v79, v73
	v_pk_add_f32 v[72:73], v[80:81], v[78:79]
	s_nop 0
	v_mul_f32_e32 v0, v67, v73
	v_pk_fma_f32 v[78:79], v[66:67], v[72:73], v[0:1] op_sel_hi:[1,1,0] neg_lo:[0,0,1] neg_hi:[0,0,1]
	v_pk_mul_f32 v[72:73], v[66:67], v[72:73] op_sel:[0,1] op_sel_hi:[1,0]
	s_waitcnt lgkmcnt(0)
	v_pk_add_f32 v[82:83], v[86:87], v[78:79]
	v_add_f32_e32 v0, v72, v73
	v_pk_add_f32 v[72:73], v[86:87], v[0:1] op_sel:[1,0] op_sel_hi:[1,0]
	ds_read2st64_b64 v[78:81], v75 offset0:8 offset1:9
	v_pk_mul_f32 v[72:73], v[70:71], v[72:73]
	s_nop 0
	v_pk_fma_f32 v[86:87], v[66:67], v[82:83], v[72:73] neg_lo:[0,0,1] neg_hi:[0,0,1]
	v_pk_fma_f32 v[72:73], v[66:67], v[82:83], v[72:73] op_sel_hi:[1,0,1]
	s_nop 0
	v_mov_b32_e32 v87, v73
	v_pk_add_f32 v[72:73], v[88:89], v[86:87]
	ds_read2st64_b64 v[86:89], v75 offset0:10 offset1:11
	v_mul_f32_e32 v0, v67, v73
	v_pk_fma_f32 v[82:83], v[66:67], v[72:73], v[0:1] op_sel_hi:[1,1,0] neg_lo:[0,0,1] neg_hi:[0,0,1]
	v_pk_mul_f32 v[72:73], v[66:67], v[72:73] op_sel:[0,1] op_sel_hi:[1,0]
	s_waitcnt lgkmcnt(1)
	v_pk_add_f32 v[82:83], v[78:79], v[82:83]
	v_add_f32_e32 v0, v72, v73
	v_pk_add_f32 v[72:73], v[78:79], v[0:1] op_sel:[1,0] op_sel_hi:[1,0]
	s_nop 0
	v_pk_mul_f32 v[72:73], v[70:71], v[72:73]
	s_nop 0
	v_pk_fma_f32 v[78:79], v[66:67], v[82:83], v[72:73] neg_lo:[0,0,1] neg_hi:[0,0,1]
	v_pk_fma_f32 v[72:73], v[66:67], v[82:83], v[72:73] op_sel_hi:[1,0,1]
	s_nop 0
	v_mov_b32_e32 v79, v73
	v_pk_add_f32 v[72:73], v[80:81], v[78:79]
	s_nop 0
	v_mul_f32_e32 v0, v67, v73
	v_pk_fma_f32 v[78:79], v[66:67], v[72:73], v[0:1] op_sel_hi:[1,1,0] neg_lo:[0,0,1] neg_hi:[0,0,1]
	v_pk_mul_f32 v[72:73], v[66:67], v[72:73] op_sel:[0,1] op_sel_hi:[1,0]
	s_waitcnt lgkmcnt(0)
	v_pk_add_f32 v[82:83], v[86:87], v[78:79]
	v_add_f32_e32 v0, v72, v73
	v_pk_add_f32 v[72:73], v[86:87], v[0:1] op_sel:[1,0] op_sel_hi:[1,0]
	ds_read2st64_b64 v[78:81], v75 offset0:12 offset1:13
	v_pk_mul_f32 v[72:73], v[70:71], v[72:73]
	s_nop 0
	v_pk_fma_f32 v[86:87], v[66:67], v[82:83], v[72:73] neg_lo:[0,0,1] neg_hi:[0,0,1]
	v_pk_fma_f32 v[72:73], v[66:67], v[82:83], v[72:73] op_sel_hi:[1,0,1]
	s_nop 0
	v_mov_b32_e32 v87, v73
	v_pk_add_f32 v[72:73], v[88:89], v[86:87]
	ds_read2st64_b64 v[86:89], v75 offset0:14 offset1:15
	v_mul_f32_e32 v0, v67, v73
	v_pk_fma_f32 v[82:83], v[66:67], v[72:73], v[0:1] op_sel_hi:[1,1,0] neg_lo:[0,0,1] neg_hi:[0,0,1]
	v_pk_mul_f32 v[72:73], v[66:67], v[72:73] op_sel:[0,1] op_sel_hi:[1,0]
	s_waitcnt lgkmcnt(1)
	v_pk_add_f32 v[82:83], v[78:79], v[82:83]
	v_add_f32_e32 v0, v72, v73
	v_pk_add_f32 v[72:73], v[78:79], v[0:1] op_sel:[1,0] op_sel_hi:[1,0]
	s_waitcnt lgkmcnt(0)
	s_waitcnt lgkmcnt(0)
	s_nop 0
	v_pk_mul_f32 v[72:73], v[70:71], v[72:73]
	s_nop 0
	v_pk_fma_f32 v[78:79], v[66:67], v[82:83], v[72:73] neg_lo:[0,0,1] neg_hi:[0,0,1]
	v_pk_fma_f32 v[72:73], v[66:67], v[82:83], v[72:73] op_sel_hi:[1,0,1]
	s_nop 0
	v_mov_b32_e32 v79, v73
	v_pk_add_f32 v[72:73], v[80:81], v[78:79]
	s_nop 0
	v_mul_f32_e32 v0, v67, v73
	v_pk_fma_f32 v[78:79], v[66:67], v[72:73], v[0:1] op_sel_hi:[1,1,0] neg_lo:[0,0,1] neg_hi:[0,0,1]
	v_pk_mul_f32 v[72:73], v[66:67], v[72:73] op_sel:[0,1] op_sel_hi:[1,0]
	s_waitcnt lgkmcnt(0)
	v_pk_add_f32 v[78:79], v[86:87], v[78:79]
	v_add_f32_e32 v0, v72, v73
	v_pk_add_f32 v[72:73], v[86:87], v[0:1] op_sel:[1,0] op_sel_hi:[1,0]
	s_nop 0
	v_pk_mul_f32 v[72:73], v[70:71], v[72:73]
	s_nop 0
	v_pk_fma_f32 v[80:81], v[66:67], v[78:79], v[72:73] neg_lo:[0,0,1] neg_hi:[0,0,1]
	v_pk_fma_f32 v[72:73], v[66:67], v[78:79], v[72:73] op_sel_hi:[1,0,1]
	s_nop 0
	v_mov_b32_e32 v81, v73
	v_pk_add_f32 v[72:73], v[88:89], v[80:81]
	s_cbranch_scc1 .LBB0_218
	s_waitcnt vmcnt(0)
	s_ashr_i32 s3, s2, 31
	s_lshl_b64 s[2:3], s[2:3], 9
	v_readlane_b32 s38, v249, 0
	v_lshl_add_u64 v[2:3], v[84:85], 0, s[2:3]
	v_readlane_b32 s39, v249, 1
	v_mov_b32_e32 v20, v189
	global_store_dwordx2 v[2:3], v[72:73], off
	s_barrier
	s_load_dwordx2 s[46:47], s[38:39], 0xf8
	v_mov_b32_e32 v4, v1
	v_mov_b32_e32 v5, v1
	v_and_b32_e32 v17, 63, v20
	v_and_b32_e32 v16, 15, v20
	s_waitcnt lgkmcnt(0)
	s_add_u32 s1, s46, s88
	s_addc_u32 s2, s47, s89
	s_add_u32 s10, s1, 0xe000000
	v_ashrrev_i32_e32 v21, 8, v20
	s_addc_u32 s11, s2, 0
	v_and_b32_e32 v14, 48, v20
	v_mov_b32_e32 v15, v1
	v_mov_b32_e32 v2, v1
	v_mov_b32_e32 v3, v1
	v_mov_b64_e32 v[8:9], v[4:5]
	v_cmp_gt_u32_e64 s[2:3], 32, v17
	v_lshl_or_b32 v46, v21, 5, v16
	v_lshl_add_u64 v[30:31], s[10:11], 0, v[14:15]
	v_mov_b64_e32 v[6:7], v[2:3]
	s_and_saveexec_b64 s[8:9], s[2:3]
	s_cbranch_execz .LBB0_221
	v_mad_i64_i32 v[6:7], s[4:5], v46, s90, v[30:31]
	v_add_co_u32_e32 v6, vcc, 0x1000, v6
	s_nop 1
	v_addc_co_u32_e32 v7, vcc, 0, v7, vcc
	global_load_dwordx4 v[6:9], v[6:7], off offset:512

; __device__ __forceinline__ float bflo_(unsigned w) { return __uint_as_float(w << 16); }
; __device__ __forceinline__ float bfhi_(unsigned w) { return __uint_as_float(w & 0xffff0000u); }
; __device__ __forceinline__ unsigned cvt_pk_bf16(float lo, float hi) { unsigned r; asm volatile("v_cvt_pk_bf16_f32 %0, %1, %2" : "=v"(r) : "v"(lo), "v"(hi)); return r; }
; #define PG8_OPQ(p) asm volatile("" : "+v"(p))
;     __device__ __forceinline__ void operator()(const f32x4 (&acc)[2][2][4][2], const Unit& u, int wr, int wc, int fr, int fq) const {
;         char* p = (char*)(HB + (size_t)(wr * 64 + fr) * ldc + u.pn * BM + wc * 32 + 8 * fq);
;         const size_t step = (size_t)16 * ldc * 2;
; #pragma unroll
;         for (int ai = 0; ai < 2; ++ai) {
;             PG8_OPQ(p);
;             u32x4 h[4][2];
; #pragma unroll
;             for (int m = 0; m < 4; ++m)
; #pragma unroll
;                 for (int bj = 0; bj < 2; ++bj) h[m][bj] = *(const u32x4*)(p + m * step + bj * HALF * 2);
; #pragma unroll
;             for (int m = 0; m < 4; ++m)
; #pragma unroll
;                 for (int bj = 0; bj < 2; ++bj) { const f32x4 v0 = acc[ai][bj][m][0], v1 = acc[ai][bj][m][1]; const u32x4 hh = h[m][bj];
;                     u32x4 w;
;                     w.x = cvt_pk_bf16(bflo_(hh.x) * alpha + v0[0], bfhi_(hh.x) * alpha + v0[1]); w.y = cvt_pk_bf16(bflo_(hh.y) * alpha + v0[2], bfhi_(hh.y) * alpha + v0[3]);
;                     w.z = cvt_pk_bf16(bflo_(hh.z) * alpha + v1[0], bfhi_(hh.z) * alpha + v1[1]); w.w = cvt_pk_bf16(bflo_(hh.w) * alpha + v1[2], bfhi_(hh.w) * alpha + v1[3]);
;                     *(u32x4*)(p + m * step + bj * HALF * 2) = w; }
;             p += 8 * step;
.LBB0_421:
	s_lshl_b32 s36, s8, 8
	v_lshl_add_u64 v[154:155], s[36:37], 1, v[148:149]
	global_load_dwordx4 v[162:165], v[154:155], off
	global_load_dwordx4 v[166:169], v[154:155], off offset:256
	v_add_co_u32_e32 v182, vcc, 0x8000, v154
	s_cmp_eq_u32 s8, 3
	s_nop 0
	v_addc_co_u32_e32 v183, vcc, 0, v155, vcc
	global_load_dwordx4 v[170:173], v[182:183], off
	global_load_dwordx4 v[174:177], v[182:183], off offset:256
	v_add_co_u32_e32 v158, vcc, 0x10000, v154
	s_mov_b64 s[8:9], -1
	s_nop 0
	v_addc_co_u32_e32 v159, vcc, 0, v155, vcc
	global_load_dwordx4 v[178:181], v[158:159], off
	global_load_dwordx4 v[138:141], v[158:159], off offset:256
	v_add_co_u32_e32 v156, vcc, 0x18000, v154
	s_waitcnt vmcnt(0) lgkmcnt(0)
	v_lshlrev_b32_e32 v184, 16, v162
	v_addc_co_u32_e32 v157, vcc, 0, v155, vcc
	global_load_dwordx4 v[134:137], v[156:157], off
	global_load_dwordx4 v[130:133], v[156:157], off offset:256
	v_and_b32_e32 v162, 0xffff0000, v162
	v_lshlrev_b32_e32 v185, 16, v163
	v_and_b32_e32 v163, 0xffff0000, v163
	v_lshlrev_b32_e32 v186, 16, v164
	v_and_b32_e32 v164, 0xffff0000, v164
	v_lshlrev_b32_e32 v187, 16, v165
	v_and_b32_e32 v165, 0xffff0000, v165
	v_fmac_f32_e32 v122, 0x3fb504f3, v184
	v_fmac_f32_e32 v123, 0x3fb504f3, v162
	v_fmac_f32_e32 v124, 0x3fb504f3, v185
	v_fmac_f32_e32 v125, 0x3fb504f3, v163
	v_fmac_f32_e32 v126, 0x3fb504f3, v186
	v_fmac_f32_e32 v127, 0x3fb504f3, v164
	v_fmac_f32_e32 v128, 0x3fb504f3, v187
	v_lshlrev_b32_e32 v188, 16, v166
	v_and_b32_e32 v166, 0xffff0000, v166
	v_lshlrev_b32_e32 v190, 16, v167
	v_and_b32_e32 v167, 0xffff0000, v167
	v_fmac_f32_e32 v129, 0x3fb504f3, v165
	v_cvt_pk_bf16_f32 v122, v122, v123
	v_cvt_pk_bf16_f32 v123, v124, v125
	v_cvt_pk_bf16_f32 v124, v126, v127
	v_cvt_pk_bf16_f32 v125, v128, v129
	v_lshlrev_b32_e32 v126, 16, v170
	v_and_b32_e32 v127, 0xffff0000, v170
	v_lshlrev_b32_e32 v128, 16, v171
	v_lshlrev_b32_e32 v162, 16, v172
	v_lshlrev_b32_e32 v192, 16, v168
	v_and_b32_e32 v168, 0xffff0000, v168
	v_lshlrev_b32_e32 v193, 16, v169
	v_and_b32_e32 v169, 0xffff0000, v169
	v_fmac_f32_e32 v118, 0x3fb504f3, v188
	v_fmac_f32_e32 v119, 0x3fb504f3, v166
	v_fmac_f32_e32 v120, 0x3fb504f3, v190
	v_fmac_f32_e32 v121, 0x3fb504f3, v167
	v_and_b32_e32 v129, 0xffff0000, v171
	v_and_b32_e32 v163, 0xffff0000, v172
	v_fmac_f32_e32 v110, 0x3fb504f3, v126
	v_fmac_f32_e32 v111, 0x3fb504f3, v127
	v_fmac_f32_e32 v112, 0x3fb504f3, v128
	v_fmac_f32_e32 v106, 0x3fb504f3, v162
	v_fmac_f32_e32 v114, 0x3fb504f3, v192
	v_fmac_f32_e32 v115, 0x3fb504f3, v168
	v_fmac_f32_e32 v116, 0x3fb504f3, v193
	v_fmac_f32_e32 v117, 0x3fb504f3, v169
	global_store_dwordx4 v[154:155], v[122:125], off
	v_cvt_pk_bf16_f32 v118, v118, v119
	v_cvt_pk_bf16_f32 v119, v120, v121
	v_cvt_pk_bf16_f32 v120, v114, v115
	v_cvt_pk_bf16_f32 v121, v116, v117
	v_fmac_f32_e32 v113, 0x3fb504f3, v129
	v_fmac_f32_e32 v107, 0x3fb504f3, v163
	global_store_dwordx4 v[154:155], v[118:121], off offset:256
	v_cvt_pk_bf16_f32 v110, v110, v111
	v_cvt_pk_bf16_f32 v111, v112, v113
	v_cvt_pk_bf16_f32 v112, v106, v107
	v_lshlrev_b32_e32 v106, 16, v174
	v_fmac_f32_e32 v102, 0x3fb504f3, v106
	v_and_b32_e32 v106, 0xffff0000, v174
	v_lshlrev_b32_e32 v164, 16, v173
	v_and_b32_e32 v165, 0xffff0000, v173
	v_fmac_f32_e32 v103, 0x3fb504f3, v106
	v_fmac_f32_e32 v108, 0x3fb504f3, v164
	v_fmac_f32_e32 v109, 0x3fb504f3, v165
	v_cvt_pk_bf16_f32 v113, v108, v109
	global_store_dwordx4 v[182:183], v[110:113], off
	v_cvt_pk_bf16_f32 v102, v102, v103
	v_lshlrev_b32_e32 v103, 16, v175
	v_fmac_f32_e32 v104, 0x3fb504f3, v103
	v_and_b32_e32 v103, 0xffff0000, v175
	v_fmac_f32_e32 v105, 0x3fb504f3, v103
	v_cvt_pk_bf16_f32 v103, v104, v105
	v_lshlrev_b32_e32 v104, 16, v176
	v_fmac_f32_e32 v98, 0x3fb504f3, v104
	v_and_b32_e32 v104, 0xffff0000, v176
	v_fmac_f32_e32 v99, 0x3fb504f3, v104
	v_cvt_pk_bf16_f32 v104, v98, v99
	v_lshlrev_b32_e32 v98, 16, v177
	v_fmac_f32_e32 v100, 0x3fb504f3, v98
	v_and_b32_e32 v98, 0xffff0000, v177
	v_fmac_f32_e32 v101, 0x3fb504f3, v98
	v_lshlrev_b32_e32 v98, 16, v178
	v_fmac_f32_e32 v94, 0x3fb504f3, v98
	v_and_b32_e32 v98, 0xffff0000, v178
	v_fmac_f32_e32 v95, 0x3fb504f3, v98
	v_cvt_pk_bf16_f32 v105, v100, v101
	global_store_dwordx4 v[182:183], v[102:105], off offset:256
	v_cvt_pk_bf16_f32 v94, v94, v95
	v_lshlrev_b32_e32 v95, 16, v179
	v_fmac_f32_e32 v96, 0x3fb504f3, v95
	v_and_b32_e32 v95, 0xffff0000, v179
	v_fmac_f32_e32 v97, 0x3fb504f3, v95
	v_cvt_pk_bf16_f32 v95, v96, v97
	v_lshlrev_b32_e32 v96, 16, v180
	v_fmac_f32_e32 v90, 0x3fb504f3, v96
	v_and_b32_e32 v96, 0xffff0000, v180
	v_fmac_f32_e32 v91, 0x3fb504f3, v96
	v_cvt_pk_bf16_f32 v96, v90, v91
	v_lshlrev_b32_e32 v90, 16, v181
	v_fmac_f32_e32 v92, 0x3fb504f3, v90
	v_and_b32_e32 v90, 0xffff0000, v181
	v_fmac_f32_e32 v93, 0x3fb504f3, v90
	v_lshlrev_b32_e32 v90, 16, v138
	v_fmac_f32_e32 v86, 0x3fb504f3, v90
	v_and_b32_e32 v90, 0xffff0000, v138
	v_fmac_f32_e32 v87, 0x3fb504f3, v90
	v_cvt_pk_bf16_f32 v97, v92, v93
	global_store_dwordx4 v[158:159], v[94:97], off
	v_cvt_pk_bf16_f32 v86, v86, v87
	v_lshlrev_b32_e32 v87, 16, v139
	v_fmac_f32_e32 v88, 0x3fb504f3, v87
	v_and_b32_e32 v87, 0xffff0000, v139
	v_fmac_f32_e32 v89, 0x3fb504f3, v87
	v_cvt_pk_bf16_f32 v87, v88, v89
	v_lshlrev_b32_e32 v88, 16, v140
	v_fmac_f32_e32 v82, 0x3fb504f3, v88
	v_and_b32_e32 v88, 0xffff0000, v140
	v_fmac_f32_e32 v83, 0x3fb504f3, v88
	v_cvt_pk_bf16_f32 v88, v82, v83
	v_lshlrev_b32_e32 v82, 16, v141
	v_fmac_f32_e32 v84, 0x3fb504f3, v82
	v_and_b32_e32 v82, 0xffff0000, v141
	v_fmac_f32_e32 v85, 0x3fb504f3, v82
	s_waitcnt vmcnt(5) lgkmcnt(0)
; __device__ __forceinline__ float bflo_(unsigned w) { return __uint_as_float(w << 16); }
; __device__ __forceinline__ float bfhi_(unsigned w) { return __uint_as_float(w & 0xffff0000u); }
; __device__ __forceinline__ unsigned cvt_pk_bf16(float lo, float hi) { unsigned r; asm volatile("v_cvt_pk_bf16_f32 %0, %1, %2" : "=v"(r) : "v"(lo), "v"(hi)); return r; }
; #define PG8_OPQ(p) asm volatile("" : "+v"(p))
;     __device__ __forceinline__ void operator()(const f32x4 (&acc)[2][2][4][2], const Unit& u, int wr, int wc, int fr, int fq) const {
;     ...
;         for (int ai = 0; ai < 2; ++ai) {
;             PG8_OPQ(p);
;             u32x4 h[4][2];
; #pragma unroll
;             for (int m = 0; m < 4; ++m)
; #pragma unroll
;                 for (int bj = 0; bj < 2; ++bj) h[m][bj] = *(const u32x4*)(p + m * step + bj * HALF * 2);
; #pragma unroll
;             for (int m = 0; m < 4; ++m)
; #pragma unroll
;                 for (int bj = 0; bj < 2; ++bj) { const f32x4 v0 = acc[ai][bj][m][0], v1 = acc[ai][bj][m][1]; const u32x4 hh = h[m][bj];
;                     u32x4 w;
;                     w.x = cvt_pk_bf16(bflo_(hh.x) * alpha + v0[0], bfhi_(hh.x) * alpha + v0[1]); w.y = cvt_pk_bf16(bflo_(hh.y) * alpha + v0[2], bfhi_(hh.y) * alpha + v0[3]);
;                     w.z = cvt_pk_bf16(bflo_(hh.z) * alpha + v1[0], bfhi_(hh.z) * alpha + v1[1]); w.w = cvt_pk_bf16(bflo_(hh.w) * alpha + v1[2], bfhi_(hh.w) * alpha + v1[3]);
;                     *(u32x4*)(p + m * step + bj * HALF * 2) = w; }
	v_lshlrev_b32_e32 v82, 16, v134
	v_fmac_f32_e32 v78, 0x3fb504f3, v82
	v_and_b32_e32 v82, 0xffff0000, v134
	v_fmac_f32_e32 v79, 0x3fb504f3, v82
	v_cvt_pk_bf16_f32 v89, v84, v85
	global_store_dwordx4 v[158:159], v[86:89], off offset:256
	v_cvt_pk_bf16_f32 v78, v78, v79
	v_lshlrev_b32_e32 v79, 16, v135
	v_fmac_f32_e32 v80, 0x3fb504f3, v79
	v_and_b32_e32 v79, 0xffff0000, v135
	v_fmac_f32_e32 v81, 0x3fb504f3, v79
	v_cvt_pk_bf16_f32 v79, v80, v81
	v_lshlrev_b32_e32 v80, 16, v136
	v_fmac_f32_e32 v74, 0x3fb504f3, v80
	v_and_b32_e32 v80, 0xffff0000, v136
	v_fmac_f32_e32 v75, 0x3fb504f3, v80
	v_cvt_pk_bf16_f32 v80, v74, v75
	v_lshlrev_b32_e32 v74, 16, v137
	v_fmac_f32_e32 v76, 0x3fb504f3, v74
	v_and_b32_e32 v74, 0xffff0000, v137
	v_fmac_f32_e32 v77, 0x3fb504f3, v74
	v_lshlrev_b32_e32 v74, 16, v130
	v_fmac_f32_e32 v70, 0x3fb504f3, v74
	v_and_b32_e32 v74, 0xffff0000, v130
	v_fmac_f32_e32 v71, 0x3fb504f3, v74
	v_cvt_pk_bf16_f32 v81, v76, v77
	global_store_dwordx4 v[156:157], v[78:81], off
	v_cvt_pk_bf16_f32 v70, v70, v71
	v_lshlrev_b32_e32 v71, 16, v131
	v_fmac_f32_e32 v72, 0x3fb504f3, v71
	v_and_b32_e32 v71, 0xffff0000, v131
	v_fmac_f32_e32 v73, 0x3fb504f3, v71
	v_cvt_pk_bf16_f32 v71, v72, v73
	v_lshlrev_b32_e32 v72, 16, v132
	v_fmac_f32_e32 v66, 0x3fb504f3, v72
	v_and_b32_e32 v72, 0xffff0000, v132
	v_fmac_f32_e32 v67, 0x3fb504f3, v72
	v_cvt_pk_bf16_f32 v72, v66, v67
	v_lshlrev_b32_e32 v66, 16, v133
	v_fmac_f32_e32 v68, 0x3fb504f3, v66
	v_and_b32_e32 v66, 0xffff0000, v133
	v_lshl_add_u64 v[100:101], v[154:155], 0, s[24:25]
	v_fmac_f32_e32 v69, 0x3fb504f3, v66
	v_cvt_pk_bf16_f32 v73, v68, v69
	global_store_dwordx4 v[156:157], v[70:73], off offset:256
	global_load_dwordx4 v[72:75], v[100:101], off
	global_load_dwordx4 v[76:79], v[100:101], off offset:256
	v_add_co_u32_e32 v102, vcc, s87, v100
	s_waitcnt vmcnt(0) lgkmcnt(0)
	v_lshlrev_b32_e32 v106, 16, v72
	v_addc_co_u32_e32 v103, vcc, 0, v101, vcc
	global_load_dwordx4 v[80:83], v[102:103], off
	global_load_dwordx4 v[84:87], v[102:103], off offset:256
	v_add_co_u32_e32 v104, vcc, s91, v100
	v_and_b32_e32 v72, 0xffff0000, v72
	s_nop 0
	v_addc_co_u32_e32 v105, vcc, 0, v101, vcc
	global_load_dwordx4 v[88:91], v[104:105], off
	global_load_dwordx4 v[92:95], v[104:105], off offset:256
	v_add_co_u32_e32 v70, vcc, s86, v100
	v_fmac_f32_e32 v62, 0x3fb504f3, v106
	s_nop 0
	v_addc_co_u32_e32 v71, vcc, 0, v101, vcc
	global_load_dwordx4 v[96:99], v[70:71], off
	global_load_dwordx4 v[66:69], v[70:71], off offset:256
	v_fmac_f32_e32 v63, 0x3fb504f3, v72
	v_cvt_pk_bf16_f32 v62, v62, v63
	v_lshlrev_b32_e32 v63, 16, v73
	v_fmac_f32_e32 v64, 0x3fb504f3, v63
	v_and_b32_e32 v63, 0xffff0000, v73
	v_fmac_f32_e32 v65, 0x3fb504f3, v63
	v_cvt_pk_bf16_f32 v63, v64, v65
	v_lshlrev_b32_e32 v64, 16, v74
	v_fmac_f32_e32 v58, 0x3fb504f3, v64
	v_and_b32_e32 v64, 0xffff0000, v74
	v_fmac_f32_e32 v59, 0x3fb504f3, v64
	v_cvt_pk_bf16_f32 v64, v58, v59
	v_lshlrev_b32_e32 v58, 16, v75
	v_fmac_f32_e32 v60, 0x3fb504f3, v58
	v_and_b32_e32 v58, 0xffff0000, v75
	v_fmac_f32_e32 v61, 0x3fb504f3, v58
	v_lshlrev_b32_e32 v58, 16, v76
	v_fmac_f32_e32 v54, 0x3fb504f3, v58
	v_and_b32_e32 v58, 0xffff0000, v76
	v_fmac_f32_e32 v55, 0x3fb504f3, v58
	v_cvt_pk_bf16_f32 v65, v60, v61
	global_store_dwordx4 v[100:101], v[62:65], off
	v_cvt_pk_bf16_f32 v54, v54, v55
	v_lshlrev_b32_e32 v55, 16, v77
	v_fmac_f32_e32 v56, 0x3fb504f3, v55
	v_and_b32_e32 v55, 0xffff0000, v77
	v_fmac_f32_e32 v57, 0x3fb504f3, v55
	v_cvt_pk_bf16_f32 v55, v56, v57
	v_lshlrev_b32_e32 v56, 16, v78
	v_fmac_f32_e32 v50, 0x3fb504f3, v56
	v_and_b32_e32 v56, 0xffff0000, v78
	v_fmac_f32_e32 v51, 0x3fb504f3, v56
	v_cvt_pk_bf16_f32 v56, v50, v51
	v_lshlrev_b32_e32 v50, 16, v79
	v_fmac_f32_e32 v52, 0x3fb504f3, v50
	v_and_b32_e32 v50, 0xffff0000, v79
	v_fmac_f32_e32 v53, 0x3fb504f3, v50
	v_cvt_pk_bf16_f32 v57, v52, v53
	global_store_dwordx4 v[100:101], v[54:57], off offset:256
	s_waitcnt vmcnt(2) lgkmcnt(0)
; __device__ __forceinline__ float bflo_(unsigned w) { return __uint_as_float(w << 16); }
; __device__ __forceinline__ float bfhi_(unsigned w) { return __uint_as_float(w & 0xffff0000u); }
; __device__ __forceinline__ unsigned cvt_pk_bf16(float lo, float hi) { unsigned r; asm volatile("v_cvt_pk_bf16_f32 %0, %1, %2" : "=v"(r) : "v"(lo), "v"(hi)); return r; }
;     __device__ __forceinline__ void operator()(const f32x4 (&acc)[2][2][4][2], const Unit& u, int wr, int wc, int fr, int fq) const {
;     ...
;             for (int m = 0; m < 4; ++m)
; #pragma unroll
;                 for (int bj = 0; bj < 2; ++bj) { const f32x4 v0 = acc[ai][bj][m][0], v1 = acc[ai][bj][m][1]; const u32x4 hh = h[m][bj];
;                     u32x4 w;
;                     w.x = cvt_pk_bf16(bflo_(hh.x) * alpha + v0[0], bfhi_(hh.x) * alpha + v0[1]); w.y = cvt_pk_bf16(bflo_(hh.y) * alpha + v0[2], bfhi_(hh.y) * alpha + v0[3]);
;                     w.z = cvt_pk_bf16(bflo_(hh.z) * alpha + v1[0], bfhi_(hh.z) * alpha + v1[1]); w.w = cvt_pk_bf16(bflo_(hh.w) * alpha + v1[2], bfhi_(hh.w) * alpha + v1[3]);
;                     *(u32x4*)(p + m * step + bj * HALF * 2) = w; }
	v_lshlrev_b32_e32 v50, 16, v80
	v_fmac_f32_e32 v46, 0x3fb504f3, v50
	v_and_b32_e32 v50, 0xffff0000, v80
	v_fmac_f32_e32 v47, 0x3fb504f3, v50
	v_cvt_pk_bf16_f32 v46, v46, v47
	v_lshlrev_b32_e32 v47, 16, v81
	v_fmac_f32_e32 v48, 0x3fb504f3, v47
	v_and_b32_e32 v47, 0xffff0000, v81
	v_fmac_f32_e32 v49, 0x3fb504f3, v47
	v_cvt_pk_bf16_f32 v47, v48, v49
	v_lshlrev_b32_e32 v48, 16, v82
	v_fmac_f32_e32 v42, 0x3fb504f3, v48
	v_and_b32_e32 v48, 0xffff0000, v82
	v_fmac_f32_e32 v43, 0x3fb504f3, v48
	v_cvt_pk_bf16_f32 v48, v42, v43
	v_lshlrev_b32_e32 v42, 16, v83
	v_fmac_f32_e32 v44, 0x3fb504f3, v42
	v_and_b32_e32 v42, 0xffff0000, v83
	v_fmac_f32_e32 v45, 0x3fb504f3, v42
	v_lshlrev_b32_e32 v42, 16, v84
	v_fmac_f32_e32 v38, 0x3fb504f3, v42
	v_and_b32_e32 v42, 0xffff0000, v84
	v_fmac_f32_e32 v39, 0x3fb504f3, v42
	v_cvt_pk_bf16_f32 v49, v44, v45
	global_store_dwordx4 v[102:103], v[46:49], off
	v_cvt_pk_bf16_f32 v38, v38, v39
	v_lshlrev_b32_e32 v39, 16, v85
	v_fmac_f32_e32 v40, 0x3fb504f3, v39
	v_and_b32_e32 v39, 0xffff0000, v85
	v_fmac_f32_e32 v41, 0x3fb504f3, v39
	v_cvt_pk_bf16_f32 v39, v40, v41
	v_lshlrev_b32_e32 v40, 16, v86
	v_fmac_f32_e32 v34, 0x3fb504f3, v40
	v_and_b32_e32 v40, 0xffff0000, v86
	v_fmac_f32_e32 v35, 0x3fb504f3, v40
	v_cvt_pk_bf16_f32 v40, v34, v35
	v_lshlrev_b32_e32 v34, 16, v87
	v_fmac_f32_e32 v36, 0x3fb504f3, v34
	v_and_b32_e32 v34, 0xffff0000, v87
	v_fmac_f32_e32 v37, 0x3fb504f3, v34
	v_lshlrev_b32_e32 v34, 16, v88
	v_fmac_f32_e32 v30, 0x3fb504f3, v34
	v_and_b32_e32 v34, 0xffff0000, v88
	v_fmac_f32_e32 v31, 0x3fb504f3, v34
	v_cvt_pk_bf16_f32 v41, v36, v37
	global_store_dwordx4 v[102:103], v[38:41], off offset:256
	v_cvt_pk_bf16_f32 v30, v30, v31
	v_lshlrev_b32_e32 v31, 16, v89
	v_fmac_f32_e32 v32, 0x3fb504f3, v31
	v_and_b32_e32 v31, 0xffff0000, v89
	v_fmac_f32_e32 v33, 0x3fb504f3, v31
	v_cvt_pk_bf16_f32 v31, v32, v33
	v_lshlrev_b32_e32 v32, 16, v90
	v_fmac_f32_e32 v26, 0x3fb504f3, v32
	v_and_b32_e32 v32, 0xffff0000, v90
	v_fmac_f32_e32 v27, 0x3fb504f3, v32
	v_cvt_pk_bf16_f32 v32, v26, v27
	v_lshlrev_b32_e32 v26, 16, v91
	v_fmac_f32_e32 v28, 0x3fb504f3, v26
	v_and_b32_e32 v26, 0xffff0000, v91
	v_fmac_f32_e32 v29, 0x3fb504f3, v26
	v_lshlrev_b32_e32 v26, 16, v92
	v_fmac_f32_e32 v22, 0x3fb504f3, v26
	v_and_b32_e32 v26, 0xffff0000, v92
	v_fmac_f32_e32 v23, 0x3fb504f3, v26
	v_cvt_pk_bf16_f32 v33, v28, v29
	global_store_dwordx4 v[104:105], v[30:33], off
	v_cvt_pk_bf16_f32 v22, v22, v23
	v_lshlrev_b32_e32 v23, 16, v93
	v_fmac_f32_e32 v24, 0x3fb504f3, v23
	v_and_b32_e32 v23, 0xffff0000, v93
	v_fmac_f32_e32 v25, 0x3fb504f3, v23
	v_cvt_pk_bf16_f32 v23, v24, v25
	v_lshlrev_b32_e32 v24, 16, v94
	v_fmac_f32_e32 v18, 0x3fb504f3, v24
	v_and_b32_e32 v24, 0xffff0000, v94
	v_fmac_f32_e32 v19, 0x3fb504f3, v24
	v_cvt_pk_bf16_f32 v24, v18, v19
	v_lshlrev_b32_e32 v18, 16, v95
	v_fmac_f32_e32 v20, 0x3fb504f3, v18
	v_and_b32_e32 v18, 0xffff0000, v95
	v_fmac_f32_e32 v21, 0x3fb504f3, v18
	v_lshlrev_b32_e32 v18, 16, v96
	v_fmac_f32_e32 v14, 0x3fb504f3, v18
	v_and_b32_e32 v18, 0xffff0000, v96
	v_fmac_f32_e32 v15, 0x3fb504f3, v18
	v_cvt_pk_bf16_f32 v25, v20, v21
	global_store_dwordx4 v[104:105], v[22:25], off offset:256
	v_cvt_pk_bf16_f32 v14, v14, v15
	v_lshlrev_b32_e32 v15, 16, v97
	v_fmac_f32_e32 v16, 0x3fb504f3, v15
	v_and_b32_e32 v15, 0xffff0000, v97
	v_fmac_f32_e32 v17, 0x3fb504f3, v15
	v_cvt_pk_bf16_f32 v15, v16, v17
	v_lshlrev_b32_e32 v16, 16, v98
	v_fmac_f32_e32 v10, 0x3fb504f3, v16
	v_and_b32_e32 v16, 0xffff0000, v98
	v_fmac_f32_e32 v11, 0x3fb504f3, v16
	v_cvt_pk_bf16_f32 v16, v10, v11
	v_lshlrev_b32_e32 v10, 16, v99
	v_fmac_f32_e32 v12, 0x3fb504f3, v10
	v_and_b32_e32 v10, 0xffff0000, v99
	v_fmac_f32_e32 v13, 0x3fb504f3, v10
	v_lshlrev_b32_e32 v10, 16, v66
	v_fmac_f32_e32 v6, 0x3fb504f3, v10
	v_and_b32_e32 v10, 0xffff0000, v66
	v_fmac_f32_e32 v7, 0x3fb504f3, v10
	v_cvt_pk_bf16_f32 v17, v12, v13
	global_store_dwordx4 v[70:71], v[14:17], off
	v_cvt_pk_bf16_f32 v6, v6, v7
	v_lshlrev_b32_e32 v7, 16, v67
	v_fmac_f32_e32 v8, 0x3fb504f3, v7
	v_and_b32_e32 v7, 0xffff0000, v67
	v_fmac_f32_e32 v9, 0x3fb504f3, v7
	v_cvt_pk_bf16_f32 v7, v8, v9
	v_lshlrev_b32_e32 v8, 16, v68
	v_fmac_f32_e32 v2, 0x3fb504f3, v8
	v_and_b32_e32 v8, 0xffff0000, v68
	v_fmac_f32_e32 v3, 0x3fb504f3, v8
	v_cvt_pk_bf16_f32 v8, v2, v3
	v_lshlrev_b32_e32 v2, 16, v69
	v_fmac_f32_e32 v4, 0x3fb504f3, v2
	v_and_b32_e32 v2, 0xffff0000, v69
	v_fmac_f32_e32 v5, 0x3fb504f3, v2
	v_cvt_pk_bf16_f32 v9, v4, v5
	global_store_dwordx4 v[70:71], v[6:9], off offset:256
	s_cbranch_scc1 .LBB0_413
	s_andn2_b64 vcc, exec, s[38:39]
	s_cbranch_vccnz .LBB0_412
	s_barrier
	s_branch .LBB0_412

; __device__ __forceinline__ float bflo_(unsigned w) { return __uint_as_float(w << 16); }
; __device__ __forceinline__ float bfhi_(unsigned w) { return __uint_as_float(w & 0xffff0000u); }
; __device__ __forceinline__ unsigned cvt_pk_bf16(float lo, float hi) { unsigned r; asm volatile("v_cvt_pk_bf16_f32 %0, %1, %2" : "=v"(r) : "v"(lo), "v"(hi)); return r; }
; #define PG8_OPQ(p) asm volatile("" : "+v"(p))
;     __device__ __forceinline__ void operator()(const f32x4 (&acc)[2][2][4][2], const Unit& u, int wr, int wc, int fr, int fq) const {
;         char* p = (char*)(HB + (size_t)(wr * 64 + fr) * ldc + u.pn * BM + wc * 32 + 8 * fq);
;         const size_t step = (size_t)16 * ldc * 2;
; #pragma unroll
;         for (int ai = 0; ai < 2; ++ai) {
;             PG8_OPQ(p);
;             u32x4 h[4][2];
; #pragma unroll
;             for (int m = 0; m < 4; ++m)
; #pragma unroll
;                 for (int bj = 0; bj < 2; ++bj) h[m][bj] = *(const u32x4*)(p + m * step + bj * HALF * 2);
; #pragma unroll
;             for (int m = 0; m < 4; ++m)
; #pragma unroll
;                 for (int bj = 0; bj < 2; ++bj) { const f32x4 v0 = acc[ai][bj][m][0], v1 = acc[ai][bj][m][1]; const u32x4 hh = h[m][bj];
;                     u32x4 w;
;                     w.x = cvt_pk_bf16(bflo_(hh.x) * alpha + v0[0], bfhi_(hh.x) * alpha + v0[1]); w.y = cvt_pk_bf16(bflo_(hh.y) * alpha + v0[2], bfhi_(hh.y) * alpha + v0[3]);
;                     w.z = cvt_pk_bf16(bflo_(hh.z) * alpha + v1[0], bfhi_(hh.z) * alpha + v1[1]); w.w = cvt_pk_bf16(bflo_(hh.w) * alpha + v1[2], bfhi_(hh.w) * alpha + v1[3]);
;                     *(u32x4*)(p + m * step + bj * HALF * 2) = w; }
;             p += 8 * step;
.LBB0_453:
	s_sub_u32 s36, 3, s8
	s_lshl_b32 s36, s36, 21
	v_lshl_add_u64 v[154:155], s[36:37], 1, v[148:149]
	global_load_dwordx4 v[162:165], v[154:155], off
	global_load_dwordx4 v[166:169], v[154:155], off offset:256
	v_add_co_u32_e32 v182, vcc, 0x8000, v154
	s_cmp_eq_u32 s8, 3
	s_nop 0
	v_addc_co_u32_e32 v183, vcc, 0, v155, vcc
	global_load_dwordx4 v[170:173], v[182:183], off
	global_load_dwordx4 v[174:177], v[182:183], off offset:256
	v_add_co_u32_e32 v158, vcc, 0x10000, v154
	s_mov_b64 s[8:9], -1
	s_nop 0
	v_addc_co_u32_e32 v159, vcc, 0, v155, vcc
	global_load_dwordx4 v[178:181], v[158:159], off
	global_load_dwordx4 v[138:141], v[158:159], off offset:256
	v_add_co_u32_e32 v156, vcc, 0x18000, v154
	s_waitcnt vmcnt(0) lgkmcnt(0)
	v_lshlrev_b32_e32 v184, 16, v162
	v_addc_co_u32_e32 v157, vcc, 0, v155, vcc
	global_load_dwordx4 v[134:137], v[156:157], off
	global_load_dwordx4 v[130:133], v[156:157], off offset:256
	v_and_b32_e32 v162, 0xffff0000, v162
	v_lshlrev_b32_e32 v185, 16, v163
	v_and_b32_e32 v163, 0xffff0000, v163
	v_lshlrev_b32_e32 v186, 16, v164
	v_and_b32_e32 v164, 0xffff0000, v164
	v_lshlrev_b32_e32 v187, 16, v165
	v_and_b32_e32 v165, 0xffff0000, v165
	v_fmac_f32_e32 v122, 0x3fb504f3, v184
	v_fmac_f32_e32 v123, 0x3fb504f3, v162
	v_fmac_f32_e32 v124, 0x3fb504f3, v185
	v_fmac_f32_e32 v125, 0x3fb504f3, v163
	v_fmac_f32_e32 v126, 0x3fb504f3, v186
	v_fmac_f32_e32 v127, 0x3fb504f3, v164
	v_fmac_f32_e32 v128, 0x3fb504f3, v187
	v_lshlrev_b32_e32 v188, 16, v166
	v_and_b32_e32 v166, 0xffff0000, v166
	v_lshlrev_b32_e32 v190, 16, v167
	v_and_b32_e32 v167, 0xffff0000, v167
	v_fmac_f32_e32 v129, 0x3fb504f3, v165
	v_cvt_pk_bf16_f32 v122, v122, v123
	v_cvt_pk_bf16_f32 v123, v124, v125
	v_cvt_pk_bf16_f32 v124, v126, v127
	v_cvt_pk_bf16_f32 v125, v128, v129
	v_lshlrev_b32_e32 v126, 16, v170
	v_and_b32_e32 v127, 0xffff0000, v170
	v_lshlrev_b32_e32 v128, 16, v171
	v_lshlrev_b32_e32 v162, 16, v172
	v_lshlrev_b32_e32 v192, 16, v168
	v_and_b32_e32 v168, 0xffff0000, v168
	v_lshlrev_b32_e32 v193, 16, v169
	v_and_b32_e32 v169, 0xffff0000, v169
	v_fmac_f32_e32 v118, 0x3fb504f3, v188
	v_fmac_f32_e32 v119, 0x3fb504f3, v166
	v_fmac_f32_e32 v120, 0x3fb504f3, v190
	v_fmac_f32_e32 v121, 0x3fb504f3, v167
	v_and_b32_e32 v129, 0xffff0000, v171
	v_and_b32_e32 v163, 0xffff0000, v172
	v_fmac_f32_e32 v110, 0x3fb504f3, v126
	v_fmac_f32_e32 v111, 0x3fb504f3, v127
	v_fmac_f32_e32 v112, 0x3fb504f3, v128
	v_fmac_f32_e32 v106, 0x3fb504f3, v162
	v_fmac_f32_e32 v114, 0x3fb504f3, v192
	v_fmac_f32_e32 v115, 0x3fb504f3, v168
	v_fmac_f32_e32 v116, 0x3fb504f3, v193
	v_fmac_f32_e32 v117, 0x3fb504f3, v169
	global_store_dwordx4 v[154:155], v[122:125], off
	v_cvt_pk_bf16_f32 v118, v118, v119
	v_cvt_pk_bf16_f32 v119, v120, v121
	v_cvt_pk_bf16_f32 v120, v114, v115
	v_cvt_pk_bf16_f32 v121, v116, v117
	v_fmac_f32_e32 v113, 0x3fb504f3, v129
	v_fmac_f32_e32 v107, 0x3fb504f3, v163
	global_store_dwordx4 v[154:155], v[118:121], off offset:256
	v_cvt_pk_bf16_f32 v110, v110, v111
	v_cvt_pk_bf16_f32 v111, v112, v113
	v_cvt_pk_bf16_f32 v112, v106, v107
	v_lshlrev_b32_e32 v106, 16, v174
	v_fmac_f32_e32 v102, 0x3fb504f3, v106
	v_and_b32_e32 v106, 0xffff0000, v174
	v_lshlrev_b32_e32 v164, 16, v173
	v_and_b32_e32 v165, 0xffff0000, v173
	v_fmac_f32_e32 v103, 0x3fb504f3, v106
	v_fmac_f32_e32 v108, 0x3fb504f3, v164
	v_fmac_f32_e32 v109, 0x3fb504f3, v165
	v_cvt_pk_bf16_f32 v113, v108, v109
	global_store_dwordx4 v[182:183], v[110:113], off
	v_cvt_pk_bf16_f32 v102, v102, v103
	v_lshlrev_b32_e32 v103, 16, v175
	v_fmac_f32_e32 v104, 0x3fb504f3, v103
	v_and_b32_e32 v103, 0xffff0000, v175
	v_fmac_f32_e32 v105, 0x3fb504f3, v103
	v_cvt_pk_bf16_f32 v103, v104, v105
	v_lshlrev_b32_e32 v104, 16, v176
	v_fmac_f32_e32 v98, 0x3fb504f3, v104
	v_and_b32_e32 v104, 0xffff0000, v176
	v_fmac_f32_e32 v99, 0x3fb504f3, v104
	v_cvt_pk_bf16_f32 v104, v98, v99
	v_lshlrev_b32_e32 v98, 16, v177
	v_fmac_f32_e32 v100, 0x3fb504f3, v98
	v_and_b32_e32 v98, 0xffff0000, v177
	v_fmac_f32_e32 v101, 0x3fb504f3, v98
	v_lshlrev_b32_e32 v98, 16, v178
	v_fmac_f32_e32 v94, 0x3fb504f3, v98
	v_and_b32_e32 v98, 0xffff0000, v178
	v_fmac_f32_e32 v95, 0x3fb504f3, v98
	v_cvt_pk_bf16_f32 v105, v100, v101
	global_store_dwordx4 v[182:183], v[102:105], off offset:256
	v_cvt_pk_bf16_f32 v94, v94, v95
	v_lshlrev_b32_e32 v95, 16, v179
	v_fmac_f32_e32 v96, 0x3fb504f3, v95
	v_and_b32_e32 v95, 0xffff0000, v179
	v_fmac_f32_e32 v97, 0x3fb504f3, v95
	v_cvt_pk_bf16_f32 v95, v96, v97
	v_lshlrev_b32_e32 v96, 16, v180
	v_fmac_f32_e32 v90, 0x3fb504f3, v96
	v_and_b32_e32 v96, 0xffff0000, v180
	v_fmac_f32_e32 v91, 0x3fb504f3, v96
	v_cvt_pk_bf16_f32 v96, v90, v91
	v_lshlrev_b32_e32 v90, 16, v181
	v_fmac_f32_e32 v92, 0x3fb504f3, v90
	v_and_b32_e32 v90, 0xffff0000, v181
	v_fmac_f32_e32 v93, 0x3fb504f3, v90
	v_lshlrev_b32_e32 v90, 16, v138
	v_fmac_f32_e32 v86, 0x3fb504f3, v90
	v_and_b32_e32 v90, 0xffff0000, v138
	v_fmac_f32_e32 v87, 0x3fb504f3, v90
	v_cvt_pk_bf16_f32 v97, v92, v93
	global_store_dwordx4 v[158:159], v[94:97], off
	v_cvt_pk_bf16_f32 v86, v86, v87
	v_lshlrev_b32_e32 v87, 16, v139
	v_fmac_f32_e32 v88, 0x3fb504f3, v87
	v_and_b32_e32 v87, 0xffff0000, v139
	v_fmac_f32_e32 v89, 0x3fb504f3, v87
	v_cvt_pk_bf16_f32 v87, v88, v89
	v_lshlrev_b32_e32 v88, 16, v140
	v_fmac_f32_e32 v82, 0x3fb504f3, v88
	v_and_b32_e32 v88, 0xffff0000, v140
	v_fmac_f32_e32 v83, 0x3fb504f3, v88
	v_cvt_pk_bf16_f32 v88, v82, v83
	v_lshlrev_b32_e32 v82, 16, v141
	v_fmac_f32_e32 v84, 0x3fb504f3, v82
	v_and_b32_e32 v82, 0xffff0000, v141
	v_fmac_f32_e32 v85, 0x3fb504f3, v82
	s_waitcnt vmcnt(5) lgkmcnt(0)
; __device__ __forceinline__ float bflo_(unsigned w) { return __uint_as_float(w << 16); }
; __device__ __forceinline__ float bfhi_(unsigned w) { return __uint_as_float(w & 0xffff0000u); }
; __device__ __forceinline__ unsigned cvt_pk_bf16(float lo, float hi) { unsigned r; asm volatile("v_cvt_pk_bf16_f32 %0, %1, %2" : "=v"(r) : "v"(lo), "v"(hi)); return r; }
; #define PG8_OPQ(p) asm volatile("" : "+v"(p))
;     __device__ __forceinline__ void operator()(const f32x4 (&acc)[2][2][4][2], const Unit& u, int wr, int wc, int fr, int fq) const {
;     ...
;         for (int ai = 0; ai < 2; ++ai) {
;             PG8_OPQ(p);
;             u32x4 h[4][2];
; #pragma unroll
;             for (int m = 0; m < 4; ++m)
; #pragma unroll
;                 for (int bj = 0; bj < 2; ++bj) h[m][bj] = *(const u32x4*)(p + m * step + bj * HALF * 2);
; #pragma unroll
;             for (int m = 0; m < 4; ++m)
; #pragma unroll
;                 for (int bj = 0; bj < 2; ++bj) { const f32x4 v0 = acc[ai][bj][m][0], v1 = acc[ai][bj][m][1]; const u32x4 hh = h[m][bj];
;                     u32x4 w;
;                     w.x = cvt_pk_bf16(bflo_(hh.x) * alpha + v0[0], bfhi_(hh.x) * alpha + v0[1]); w.y = cvt_pk_bf16(bflo_(hh.y) * alpha + v0[2], bfhi_(hh.y) * alpha + v0[3]);
;                     w.z = cvt_pk_bf16(bflo_(hh.z) * alpha + v1[0], bfhi_(hh.z) * alpha + v1[1]); w.w = cvt_pk_bf16(bflo_(hh.w) * alpha + v1[2], bfhi_(hh.w) * alpha + v1[3]);
;                     *(u32x4*)(p + m * step + bj * HALF * 2) = w; }
	v_lshlrev_b32_e32 v82, 16, v134
	v_fmac_f32_e32 v78, 0x3fb504f3, v82
	v_and_b32_e32 v82, 0xffff0000, v134
	v_fmac_f32_e32 v79, 0x3fb504f3, v82
	v_cvt_pk_bf16_f32 v89, v84, v85
	global_store_dwordx4 v[158:159], v[86:89], off offset:256
	v_cvt_pk_bf16_f32 v78, v78, v79
	v_lshlrev_b32_e32 v79, 16, v135
	v_fmac_f32_e32 v80, 0x3fb504f3, v79
	v_and_b32_e32 v79, 0xffff0000, v135
	v_fmac_f32_e32 v81, 0x3fb504f3, v79
	v_cvt_pk_bf16_f32 v79, v80, v81
	v_lshlrev_b32_e32 v80, 16, v136
	v_fmac_f32_e32 v74, 0x3fb504f3, v80
	v_and_b32_e32 v80, 0xffff0000, v136
	v_fmac_f32_e32 v75, 0x3fb504f3, v80
	v_cvt_pk_bf16_f32 v80, v74, v75
	v_lshlrev_b32_e32 v74, 16, v137
	v_fmac_f32_e32 v76, 0x3fb504f3, v74
	v_and_b32_e32 v74, 0xffff0000, v137
	v_fmac_f32_e32 v77, 0x3fb504f3, v74
	v_lshlrev_b32_e32 v74, 16, v130
	v_fmac_f32_e32 v70, 0x3fb504f3, v74
	v_and_b32_e32 v74, 0xffff0000, v130
	v_fmac_f32_e32 v71, 0x3fb504f3, v74
	v_cvt_pk_bf16_f32 v81, v76, v77
	global_store_dwordx4 v[156:157], v[78:81], off
	v_cvt_pk_bf16_f32 v70, v70, v71
	v_lshlrev_b32_e32 v71, 16, v131
	v_fmac_f32_e32 v72, 0x3fb504f3, v71
	v_and_b32_e32 v71, 0xffff0000, v131
	v_fmac_f32_e32 v73, 0x3fb504f3, v71
	v_cvt_pk_bf16_f32 v71, v72, v73
	v_lshlrev_b32_e32 v72, 16, v132
	v_fmac_f32_e32 v66, 0x3fb504f3, v72
	v_and_b32_e32 v72, 0xffff0000, v132
	v_fmac_f32_e32 v67, 0x3fb504f3, v72
	v_cvt_pk_bf16_f32 v72, v66, v67
	v_lshlrev_b32_e32 v66, 16, v133
	v_fmac_f32_e32 v68, 0x3fb504f3, v66
	v_and_b32_e32 v66, 0xffff0000, v133
	v_lshl_add_u64 v[100:101], v[154:155], 0, s[24:25]
	v_fmac_f32_e32 v69, 0x3fb504f3, v66
	v_cvt_pk_bf16_f32 v73, v68, v69
	global_store_dwordx4 v[156:157], v[70:73], off offset:256
	global_load_dwordx4 v[72:75], v[100:101], off
	global_load_dwordx4 v[76:79], v[100:101], off offset:256
	v_add_co_u32_e32 v102, vcc, s87, v100
	s_waitcnt vmcnt(0) lgkmcnt(0)
	v_lshlrev_b32_e32 v106, 16, v72
	v_addc_co_u32_e32 v103, vcc, 0, v101, vcc
	global_load_dwordx4 v[80:83], v[102:103], off
	global_load_dwordx4 v[84:87], v[102:103], off offset:256
	v_add_co_u32_e32 v104, vcc, s91, v100
	v_and_b32_e32 v72, 0xffff0000, v72
	s_nop 0
	v_addc_co_u32_e32 v105, vcc, 0, v101, vcc
	global_load_dwordx4 v[88:91], v[104:105], off
	global_load_dwordx4 v[92:95], v[104:105], off offset:256
	v_add_co_u32_e32 v70, vcc, s86, v100
	v_fmac_f32_e32 v62, 0x3fb504f3, v106
	s_nop 0
	v_addc_co_u32_e32 v71, vcc, 0, v101, vcc
	global_load_dwordx4 v[96:99], v[70:71], off
	global_load_dwordx4 v[66:69], v[70:71], off offset:256
	v_fmac_f32_e32 v63, 0x3fb504f3, v72
	v_cvt_pk_bf16_f32 v62, v62, v63
	v_lshlrev_b32_e32 v63, 16, v73
	v_fmac_f32_e32 v64, 0x3fb504f3, v63
	v_and_b32_e32 v63, 0xffff0000, v73
	v_fmac_f32_e32 v65, 0x3fb504f3, v63
	v_cvt_pk_bf16_f32 v63, v64, v65
	v_lshlrev_b32_e32 v64, 16, v74
	v_fmac_f32_e32 v58, 0x3fb504f3, v64
	v_and_b32_e32 v64, 0xffff0000, v74
	v_fmac_f32_e32 v59, 0x3fb504f3, v64
	v_cvt_pk_bf16_f32 v64, v58, v59
	v_lshlrev_b32_e32 v58, 16, v75
	v_fmac_f32_e32 v60, 0x3fb504f3, v58
	v_and_b32_e32 v58, 0xffff0000, v75
	v_fmac_f32_e32 v61, 0x3fb504f3, v58
	v_lshlrev_b32_e32 v58, 16, v76
	v_fmac_f32_e32 v54, 0x3fb504f3, v58
	v_and_b32_e32 v58, 0xffff0000, v76
	v_fmac_f32_e32 v55, 0x3fb504f3, v58
	v_cvt_pk_bf16_f32 v65, v60, v61
	global_store_dwordx4 v[100:101], v[62:65], off
	v_cvt_pk_bf16_f32 v54, v54, v55
	v_lshlrev_b32_e32 v55, 16, v77
	v_fmac_f32_e32 v56, 0x3fb504f3, v55
	v_and_b32_e32 v55, 0xffff0000, v77
	v_fmac_f32_e32 v57, 0x3fb504f3, v55
	v_cvt_pk_bf16_f32 v55, v56, v57
	v_lshlrev_b32_e32 v56, 16, v78
	v_fmac_f32_e32 v50, 0x3fb504f3, v56
	v_and_b32_e32 v56, 0xffff0000, v78
	v_fmac_f32_e32 v51, 0x3fb504f3, v56
	v_cvt_pk_bf16_f32 v56, v50, v51
	v_lshlrev_b32_e32 v50, 16, v79
	v_fmac_f32_e32 v52, 0x3fb504f3, v50
	v_and_b32_e32 v50, 0xffff0000, v79
	v_fmac_f32_e32 v53, 0x3fb504f3, v50
	v_cvt_pk_bf16_f32 v57, v52, v53
	global_store_dwordx4 v[100:101], v[54:57], off offset:256
	s_waitcnt vmcnt(2) lgkmcnt(0)
; __device__ __forceinline__ float bflo_(unsigned w) { return __uint_as_float(w << 16); }
; __device__ __forceinline__ float bfhi_(unsigned w) { return __uint_as_float(w & 0xffff0000u); }
; __device__ __forceinline__ unsigned cvt_pk_bf16(float lo, float hi) { unsigned r; asm volatile("v_cvt_pk_bf16_f32 %0, %1, %2" : "=v"(r) : "v"(lo), "v"(hi)); return r; }
;     __device__ __forceinline__ void operator()(const f32x4 (&acc)[2][2][4][2], const Unit& u, int wr, int wc, int fr, int fq) const {
;     ...
;             for (int m = 0; m < 4; ++m)
; #pragma unroll
;                 for (int bj = 0; bj < 2; ++bj) { const f32x4 v0 = acc[ai][bj][m][0], v1 = acc[ai][bj][m][1]; const u32x4 hh = h[m][bj];
;                     u32x4 w;
;                     w.x = cvt_pk_bf16(bflo_(hh.x) * alpha + v0[0], bfhi_(hh.x) * alpha + v0[1]); w.y = cvt_pk_bf16(bflo_(hh.y) * alpha + v0[2], bfhi_(hh.y) * alpha + v0[3]);
;                     w.z = cvt_pk_bf16(bflo_(hh.z) * alpha + v1[0], bfhi_(hh.z) * alpha + v1[1]); w.w = cvt_pk_bf16(bflo_(hh.w) * alpha + v1[2], bfhi_(hh.w) * alpha + v1[3]);
;                     *(u32x4*)(p + m * step + bj * HALF * 2) = w; }
	v_lshlrev_b32_e32 v50, 16, v80
	v_fmac_f32_e32 v46, 0x3fb504f3, v50
	v_and_b32_e32 v50, 0xffff0000, v80
	v_fmac_f32_e32 v47, 0x3fb504f3, v50
	v_cvt_pk_bf16_f32 v46, v46, v47
	v_lshlrev_b32_e32 v47, 16, v81
	v_fmac_f32_e32 v48, 0x3fb504f3, v47
	v_and_b32_e32 v47, 0xffff0000, v81
	v_fmac_f32_e32 v49, 0x3fb504f3, v47
	v_cvt_pk_bf16_f32 v47, v48, v49
	v_lshlrev_b32_e32 v48, 16, v82
	v_fmac_f32_e32 v42, 0x3fb504f3, v48
	v_and_b32_e32 v48, 0xffff0000, v82
	v_fmac_f32_e32 v43, 0x3fb504f3, v48
	v_cvt_pk_bf16_f32 v48, v42, v43
	v_lshlrev_b32_e32 v42, 16, v83
	v_fmac_f32_e32 v44, 0x3fb504f3, v42
	v_and_b32_e32 v42, 0xffff0000, v83
	v_fmac_f32_e32 v45, 0x3fb504f3, v42
	v_lshlrev_b32_e32 v42, 16, v84
	v_fmac_f32_e32 v38, 0x3fb504f3, v42
	v_and_b32_e32 v42, 0xffff0000, v84
	v_fmac_f32_e32 v39, 0x3fb504f3, v42
	v_cvt_pk_bf16_f32 v49, v44, v45
	global_store_dwordx4 v[102:103], v[46:49], off
	v_cvt_pk_bf16_f32 v38, v38, v39
	v_lshlrev_b32_e32 v39, 16, v85
	v_fmac_f32_e32 v40, 0x3fb504f3, v39
	v_and_b32_e32 v39, 0xffff0000, v85
	v_fmac_f32_e32 v41, 0x3fb504f3, v39
	v_cvt_pk_bf16_f32 v39, v40, v41
	v_lshlrev_b32_e32 v40, 16, v86
	v_fmac_f32_e32 v34, 0x3fb504f3, v40
	v_and_b32_e32 v40, 0xffff0000, v86
	v_fmac_f32_e32 v35, 0x3fb504f3, v40
	v_cvt_pk_bf16_f32 v40, v34, v35
	v_lshlrev_b32_e32 v34, 16, v87
	v_fmac_f32_e32 v36, 0x3fb504f3, v34
	v_and_b32_e32 v34, 0xffff0000, v87
	v_fmac_f32_e32 v37, 0x3fb504f3, v34
	v_lshlrev_b32_e32 v34, 16, v88
	v_fmac_f32_e32 v30, 0x3fb504f3, v34
	v_and_b32_e32 v34, 0xffff0000, v88
	v_fmac_f32_e32 v31, 0x3fb504f3, v34
	v_cvt_pk_bf16_f32 v41, v36, v37
	global_store_dwordx4 v[102:103], v[38:41], off offset:256
	v_cvt_pk_bf16_f32 v30, v30, v31
	v_lshlrev_b32_e32 v31, 16, v89
	v_fmac_f32_e32 v32, 0x3fb504f3, v31
	v_and_b32_e32 v31, 0xffff0000, v89
	v_fmac_f32_e32 v33, 0x3fb504f3, v31
	v_cvt_pk_bf16_f32 v31, v32, v33
	v_lshlrev_b32_e32 v32, 16, v90
	v_fmac_f32_e32 v26, 0x3fb504f3, v32
	v_and_b32_e32 v32, 0xffff0000, v90
	v_fmac_f32_e32 v27, 0x3fb504f3, v32
	v_cvt_pk_bf16_f32 v32, v26, v27
	v_lshlrev_b32_e32 v26, 16, v91
	v_fmac_f32_e32 v28, 0x3fb504f3, v26
	v_and_b32_e32 v26, 0xffff0000, v91
	v_fmac_f32_e32 v29, 0x3fb504f3, v26
	v_lshlrev_b32_e32 v26, 16, v92
	v_fmac_f32_e32 v22, 0x3fb504f3, v26
	v_and_b32_e32 v26, 0xffff0000, v92
	v_fmac_f32_e32 v23, 0x3fb504f3, v26
	v_cvt_pk_bf16_f32 v33, v28, v29
	global_store_dwordx4 v[104:105], v[30:33], off
	v_cvt_pk_bf16_f32 v22, v22, v23
	v_lshlrev_b32_e32 v23, 16, v93
	v_fmac_f32_e32 v24, 0x3fb504f3, v23
	v_and_b32_e32 v23, 0xffff0000, v93
	v_fmac_f32_e32 v25, 0x3fb504f3, v23
	v_cvt_pk_bf16_f32 v23, v24, v25
	v_lshlrev_b32_e32 v24, 16, v94
	v_fmac_f32_e32 v18, 0x3fb504f3, v24
	v_and_b32_e32 v24, 0xffff0000, v94
	v_fmac_f32_e32 v19, 0x3fb504f3, v24
	v_cvt_pk_bf16_f32 v24, v18, v19
	v_lshlrev_b32_e32 v18, 16, v95
	v_fmac_f32_e32 v20, 0x3fb504f3, v18
	v_and_b32_e32 v18, 0xffff0000, v95
	v_fmac_f32_e32 v21, 0x3fb504f3, v18
	v_lshlrev_b32_e32 v18, 16, v96
	v_fmac_f32_e32 v14, 0x3fb504f3, v18
	v_and_b32_e32 v18, 0xffff0000, v96
	v_fmac_f32_e32 v15, 0x3fb504f3, v18
	v_cvt_pk_bf16_f32 v25, v20, v21
	global_store_dwordx4 v[104:105], v[22:25], off offset:256
	v_cvt_pk_bf16_f32 v14, v14, v15
	v_lshlrev_b32_e32 v15, 16, v97
	v_fmac_f32_e32 v16, 0x3fb504f3, v15
	v_and_b32_e32 v15, 0xffff0000, v97
	v_fmac_f32_e32 v17, 0x3fb504f3, v15
	v_cvt_pk_bf16_f32 v15, v16, v17
	v_lshlrev_b32_e32 v16, 16, v98
	v_fmac_f32_e32 v10, 0x3fb504f3, v16
	v_and_b32_e32 v16, 0xffff0000, v98
	v_fmac_f32_e32 v11, 0x3fb504f3, v16
	v_cvt_pk_bf16_f32 v16, v10, v11
	v_lshlrev_b32_e32 v10, 16, v99
	v_fmac_f32_e32 v12, 0x3fb504f3, v10
	v_and_b32_e32 v10, 0xffff0000, v99
	v_fmac_f32_e32 v13, 0x3fb504f3, v10
	v_lshlrev_b32_e32 v10, 16, v66
	v_fmac_f32_e32 v6, 0x3fb504f3, v10
	v_and_b32_e32 v10, 0xffff0000, v66
	v_fmac_f32_e32 v7, 0x3fb504f3, v10
	v_cvt_pk_bf16_f32 v17, v12, v13
	global_store_dwordx4 v[70:71], v[14:17], off
	v_cvt_pk_bf16_f32 v6, v6, v7
	v_lshlrev_b32_e32 v7, 16, v67
	v_fmac_f32_e32 v8, 0x3fb504f3, v7
	v_and_b32_e32 v7, 0xffff0000, v67
	v_fmac_f32_e32 v9, 0x3fb504f3, v7
	v_cvt_pk_bf16_f32 v7, v8, v9
	v_lshlrev_b32_e32 v8, 16, v68
	v_fmac_f32_e32 v2, 0x3fb504f3, v8
	v_and_b32_e32 v8, 0xffff0000, v68
	v_fmac_f32_e32 v3, 0x3fb504f3, v8
	v_cvt_pk_bf16_f32 v8, v2, v3
	v_lshlrev_b32_e32 v2, 16, v69
	v_fmac_f32_e32 v4, 0x3fb504f3, v2
	v_and_b32_e32 v2, 0xffff0000, v69
	v_fmac_f32_e32 v5, 0x3fb504f3, v2
	v_cvt_pk_bf16_f32 v9, v4, v5
	global_store_dwordx4 v[70:71], v[6:9], off offset:256
	s_cbranch_scc1 .LBB0_445
	s_andn2_b64 vcc, exec, s[26:27]
	s_cbranch_vccnz .LBB0_444
	s_barrier
	s_branch .LBB0_444
